# A/B: all per-segment s_setprio flips deleted from the 5 GEMM K-loops (both halves at equal priority)
# speedup vs baseline: 1.0061x; 1.0023x over previous
; #define PG8_STAGE(bufoff, gbase, voff) do { _Pragma("unroll") for (int _i = 0; _i < 2; ++_i) \
;         __builtin_amdgcn_global_load_lds((const unsigned*)((const char*)(gbase) + (voff)[_i]), (PG8_LAS unsigned*)(lds + (bufoff) + ldsw + _i * 8192), 16, 0, 0); } while (0)
; #define PG8_LDA(dst, b, h) do { _Pragma("unroll") for (int m = 0; m < 4; ++m) _Pragma("unroll") for (int k = 0; k < 2; ++k) dst[m][k] = *(const PG8_LAS bf16x8*)(lds + PG8_SA(b, h) + aoff + m * 2048 + k * 1024); } while (0)
; #define PG8_LDB(dst, b, h) do { _Pragma("unroll") for (int n = 0; n < 2; ++n) _Pragma("unroll") for (int k = 0; k < 2; ++k) dst[n][k] = *(const PG8_LAS bf16x8*)(lds + PG8_SB(b, h) + boff + n * 2048 + k * 1024); } while (0)
; #define PG8_MMA(ai, bj, At, Bt) do { __builtin_amdgcn_s_setprio(1); _Pragma("unroll") for (int m = 0; m < 4; ++m) _Pragma("unroll") for (int n = 0; n < 2; ++n) _Pragma("unroll") for (int k = 0; k < 2; ++k) \
;         acc[ai][bj][m][n] = __builtin_amdgcn_mfma_f32_16x16x32_bf16(Bt[n][k], At[m][k], acc[ai][bj][m][n], 0, 0, 0); __builtin_amdgcn_s_setprio(0); } while (0)
; #define PG8_WAIT_V(n) asm volatile("s_waitcnt vmcnt(" #n ")" ::: "memory")
; #define PG8_WAIT_L(n) asm volatile("s_waitcnt lgkmcnt(" #n ")" ::: "memory")
; #define PG8_BAR __builtin_amdgcn_s_barrier()
; template <class Epi, class Sched, bool ALIGN_EPI = false, bool SP2 = false>
; __device__ __forceinline__ void gemm_phase(PG8_LAS unsigned char* lds, const Gemm g, const Sched& S, const Epi& E) {
;     ...
;             const char* a1 = cA + (size_t)(t + 1) * kstep;
;             const char* a2 = last ? nA : cA + (size_t)(t + 2) * kstep; const char* b2 = last ? nB : cB + (size_t)(t + 2) * kstep;
;             const char* a3 = a2 + kstep; const char* b3 = b2 + kstep;
;             if (last && has_next) S.a_ready(nxt);
;             if constexpr (SP2) {
;             PG8_LDB(B0, 0, 0); PG8_LDB(B1, 0, 1); PG8_SCHED; PG8_LDA(At, 0, 0); PG8_STAGE(PG8_SA(1, 1), a1 + hstep, voffA);
;             PG8_WAIT_V(8); PG8_WAIT_L(0); PG8_BAR; PG8_MMA(0, 0, At, B0); PG8_MMA(0, 1, At, B1); PG8_BAR; PG8_SCHED;
;             PG8_LDA(At, 0, 1); PG8_STAGE(PG8_SB(0, 0), b2, voffB); PG8_STAGE(PG8_SB(0, 1), b2 + hstep, voffB); PG8_STAGE(PG8_SA(0, 0), a2, voffA);
;             PG8_WAIT_V(8); PG8_WAIT_L(0); PG8_BAR; PG8_MMA(1, 0, At, B0); PG8_MMA(1, 1, At, B1); PG8_BAR; PG8_SCHED;
.LBB0_25:
	s_add_i32 s88, 0, 0x10000
	s_add_i32 s90, 0, 0x14000
	ds_read_b128 v[142:145], v200
	ds_read_b128 v[146:149], v200 offset:1024
	ds_read_b128 v[150:153], v200 offset:2048
	ds_read_b128 v[154:157], v200 offset:3072
	ds_read_b128 v[164:167], v200 offset:16384
	ds_read_b128 v[168:171], v200 offset:17408
	ds_read_b128 v[172:175], v200 offset:18432
	ds_read_b128 v[176:179], v200 offset:19456
	s_add_i32 m0, s29, 0xc000
	ds_read_b128 v[180:183], v141
	ds_read_b128 v[184:187], v141 offset:1024
	ds_read_b128 v[188:191], v141 offset:2048
	ds_read_b128 v[192:195], v141 offset:3072
	ds_read_b128 v[196:199], v141 offset:4096
	ds_read_b128 v[222:225], v141 offset:5120
	ds_read_b128 v[226:229], v141 offset:6144
	ds_read_b128 v[230:233], v141 offset:7168
	global_load_lds_dwordx4 v134, s[80:81]
	s_add_i32 m0, s29, 0xe000
	s_nop 0
	global_load_lds_dwordx4 v136, s[80:81]
	s_add_u32 s4, s80, 0xfff80080
	s_addc_u32 s5, s81, -1
	s_cmp_eq_u32 s87, 28
	s_cselect_b32 s53, s55, s5
	s_cselect_b32 s52, s83, s4
	s_cselect_b32 s5, s73, s86
	s_cselect_b32 s4, s84, s85
	s_waitcnt vmcnt(8)
	s_waitcnt lgkmcnt(0)
	s_barrier
	s_waitcnt lgkmcnt(0)
	v_mfma_f32_16x16x32_bf16 v[124:127], v[142:145], v[180:183], v[124:127]
	v_mfma_f32_16x16x32_bf16 v[120:123], v[150:153], v[180:183], v[120:123]
	v_mfma_f32_16x16x32_bf16 v[116:119], v[142:145], v[188:191], v[116:119]
	v_mfma_f32_16x16x32_bf16 v[112:115], v[150:153], v[188:191], v[112:115]
	v_mfma_f32_16x16x32_bf16 v[100:103], v[142:145], v[196:199], v[100:103]
	v_mfma_f32_16x16x32_bf16 v[96:99], v[150:153], v[196:199], v[96:99]
	v_mfma_f32_16x16x32_bf16 v[84:87], v[142:145], v[226:229], v[84:87]
	v_mfma_f32_16x16x32_bf16 v[80:83], v[150:153], v[226:229], v[80:83]
	v_mfma_f32_16x16x32_bf16 v[124:127], v[146:149], v[184:187], v[124:127]
	v_mfma_f32_16x16x32_bf16 v[120:123], v[154:157], v[184:187], v[120:123]
	v_mfma_f32_16x16x32_bf16 v[116:119], v[146:149], v[192:195], v[116:119]
	v_mfma_f32_16x16x32_bf16 v[112:115], v[154:157], v[192:195], v[112:115]
	v_mfma_f32_16x16x32_bf16 v[100:103], v[146:149], v[222:225], v[100:103]
	v_mfma_f32_16x16x32_bf16 v[96:99], v[154:157], v[222:225], v[96:99]
	v_mfma_f32_16x16x32_bf16 v[84:87], v[146:149], v[230:233], v[84:87]
	v_mfma_f32_16x16x32_bf16 v[80:83], v[154:157], v[230:233], v[80:83]
	v_mfma_f32_16x16x32_bf16 v[108:111], v[164:167], v[180:183], v[108:111]
	v_mfma_f32_16x16x32_bf16 v[104:107], v[172:175], v[180:183], v[104:107]
	v_mfma_f32_16x16x32_bf16 v[92:95], v[164:167], v[188:191], v[92:95]
	v_mfma_f32_16x16x32_bf16 v[88:91], v[172:175], v[188:191], v[88:91]
	v_mfma_f32_16x16x32_bf16 v[76:79], v[164:167], v[196:199], v[76:79]
	v_mfma_f32_16x16x32_bf16 v[72:75], v[172:175], v[196:199], v[72:75]
	v_mfma_f32_16x16x32_bf16 v[68:71], v[164:167], v[226:229], v[68:71]
	v_mfma_f32_16x16x32_bf16 v[64:67], v[172:175], v[226:229], v[64:67]
	v_mfma_f32_16x16x32_bf16 v[108:111], v[168:171], v[184:187], v[108:111]
	v_mfma_f32_16x16x32_bf16 v[104:107], v[176:179], v[184:187], v[104:107]
	v_mfma_f32_16x16x32_bf16 v[92:95], v[168:171], v[192:195], v[92:95]
	v_mfma_f32_16x16x32_bf16 v[88:91], v[176:179], v[192:195], v[88:91]
	v_mfma_f32_16x16x32_bf16 v[76:79], v[168:171], v[222:225], v[76:79]
	v_mfma_f32_16x16x32_bf16 v[72:75], v[176:179], v[222:225], v[72:75]
	v_mfma_f32_16x16x32_bf16 v[68:71], v[168:171], v[230:233], v[68:71]
	v_mfma_f32_16x16x32_bf16 v[64:67], v[176:179], v[230:233], v[64:67]
	s_barrier
	s_add_i32 s88, s88, s28
	s_mov_b32 m0, s88
	ds_read_b128 v[180:183], v141 offset:16384
	ds_read_b128 v[184:187], v141 offset:17408
	ds_read_b128 v[188:191], v141 offset:18432
	ds_read_b128 v[192:195], v141 offset:19456
	ds_read_b128 v[196:199], v141 offset:20480
	ds_read_b128 v[222:225], v141 offset:21504
	ds_read_b128 v[226:229], v141 offset:22528
	ds_read_b128 v[230:233], v141 offset:23552
	global_load_lds_dwordx4 v160, s[4:5]
	s_add_i32 m0, s88, 0x2000
	s_add_u32 s88, s4, 0x80000
	s_addc_u32 s89, s5, 0
	s_add_i32 s90, s90, s28
	global_load_lds_dwordx4 v128, s[4:5]
	s_mov_b32 m0, s90
	s_nop 0
	global_load_lds_dwordx4 v160, s[88:89]
	s_add_i32 m0, s90, 0x2000
	s_nop 0
	global_load_lds_dwordx4 v128, s[88:89]
	s_mov_b32 m0, s29
	s_nop 0
	global_load_lds_dwordx4 v132, s[52:53]
	s_mov_b32 m0, s45
	s_nop 0
	global_load_lds_dwordx4 v130, s[52:53]
	s_add_u32 s98, s52, 0x80
	s_addc_u32 s99, s53, 0
	s_waitcnt vmcnt(8)
	s_waitcnt lgkmcnt(0)
	s_barrier
	s_waitcnt lgkmcnt(0)
	v_mfma_f32_16x16x32_bf16 v[60:63], v[142:145], v[180:183], v[60:63]
	v_mfma_f32_16x16x32_bf16 v[56:59], v[150:153], v[180:183], v[56:59]
	v_mfma_f32_16x16x32_bf16 v[52:55], v[142:145], v[188:191], v[52:55]
	v_mfma_f32_16x16x32_bf16 v[48:51], v[150:153], v[188:191], v[48:51]
	v_mfma_f32_16x16x32_bf16 v[36:39], v[142:145], v[196:199], v[36:39]
	v_mfma_f32_16x16x32_bf16 v[32:35], v[150:153], v[196:199], v[32:35]
	v_mfma_f32_16x16x32_bf16 v[20:23], v[142:145], v[226:229], v[20:23]
	v_mfma_f32_16x16x32_bf16 v[16:19], v[150:153], v[226:229], v[16:19]
	v_mfma_f32_16x16x32_bf16 v[60:63], v[146:149], v[184:187], v[60:63]
	v_mfma_f32_16x16x32_bf16 v[56:59], v[154:157], v[184:187], v[56:59]
	v_mfma_f32_16x16x32_bf16 v[52:55], v[146:149], v[192:195], v[52:55]
	v_mfma_f32_16x16x32_bf16 v[48:51], v[154:157], v[192:195], v[48:51]
	v_mfma_f32_16x16x32_bf16 v[36:39], v[146:149], v[222:225], v[36:39]
	v_mfma_f32_16x16x32_bf16 v[32:35], v[154:157], v[222:225], v[32:35]
	v_mfma_f32_16x16x32_bf16 v[20:23], v[146:149], v[230:233], v[20:23]
	v_mfma_f32_16x16x32_bf16 v[16:19], v[154:157], v[230:233], v[16:19]
	v_mfma_f32_16x16x32_bf16 v[44:47], v[164:167], v[180:183], v[44:47]
	v_mfma_f32_16x16x32_bf16 v[40:43], v[172:175], v[180:183], v[40:43]
	v_mfma_f32_16x16x32_bf16 v[28:31], v[164:167], v[188:191], v[28:31]
	v_mfma_f32_16x16x32_bf16 v[24:27], v[172:175], v[188:191], v[24:27]
	v_mfma_f32_16x16x32_bf16 v[12:15], v[164:167], v[196:199], v[12:15]
	v_mfma_f32_16x16x32_bf16 v[8:11], v[172:175], v[196:199], v[8:11]
	v_mfma_f32_16x16x32_bf16 v[4:7], v[164:167], v[226:229], v[4:7]
	v_mfma_f32_16x16x32_bf16 v[0:3], v[172:175], v[226:229], v[0:3]
	v_mfma_f32_16x16x32_bf16 v[44:47], v[168:171], v[184:187], v[44:47]
	v_mfma_f32_16x16x32_bf16 v[40:43], v[176:179], v[184:187], v[40:43]
	v_mfma_f32_16x16x32_bf16 v[28:31], v[168:171], v[192:195], v[28:31]
	v_mfma_f32_16x16x32_bf16 v[24:27], v[176:179], v[192:195], v[24:27]
	v_mfma_f32_16x16x32_bf16 v[12:15], v[168:171], v[222:225], v[12:15]
	v_mfma_f32_16x16x32_bf16 v[8:11], v[176:179], v[222:225], v[8:11]
	v_mfma_f32_16x16x32_bf16 v[4:7], v[168:171], v[230:233], v[4:7]
	v_mfma_f32_16x16x32_bf16 v[0:3], v[176:179], v[230:233], v[0:3]
	s_barrier
; #define PG8_STAGE(bufoff, gbase, voff) do { _Pragma("unroll") for (int _i = 0; _i < 2; ++_i) \
;         __builtin_amdgcn_global_load_lds((const unsigned*)((const char*)(gbase) + (voff)[_i]), (PG8_LAS unsigned*)(lds + (bufoff) + ldsw + _i * 8192), 16, 0, 0); } while (0)
; #define PG8_LDA(dst, b, h) do { _Pragma("unroll") for (int m = 0; m < 4; ++m) _Pragma("unroll") for (int k = 0; k < 2; ++k) dst[m][k] = *(const PG8_LAS bf16x8*)(lds + PG8_SA(b, h) + aoff + m * 2048 + k * 1024); } while (0)
; #define PG8_LDB(dst, b, h) do { _Pragma("unroll") for (int n = 0; n < 2; ++n) _Pragma("unroll") for (int k = 0; k < 2; ++k) dst[n][k] = *(const PG8_LAS bf16x8*)(lds + PG8_SB(b, h) + boff + n * 2048 + k * 1024); } while (0)
; #define PG8_MMA(ai, bj, At, Bt) do { __builtin_amdgcn_s_setprio(1); _Pragma("unroll") for (int m = 0; m < 4; ++m) _Pragma("unroll") for (int n = 0; n < 2; ++n) _Pragma("unroll") for (int k = 0; k < 2; ++k) \
;         acc[ai][bj][m][n] = __builtin_amdgcn_mfma_f32_16x16x32_bf16(Bt[n][k], At[m][k], acc[ai][bj][m][n], 0, 0, 0); __builtin_amdgcn_s_setprio(0); } while (0)
; #define PG8_WAIT_V(n) asm volatile("s_waitcnt vmcnt(" #n ")" ::: "memory")
; #define PG8_WAIT_L(n) asm volatile("s_waitcnt lgkmcnt(" #n ")" ::: "memory")
; #define PG8_BAR __builtin_amdgcn_s_barrier()
; #define PG8_SCHED __builtin_amdgcn_sched_barrier(0)
; template <class Epi, class Sched, bool ALIGN_EPI = false, bool SP2 = false>
; __device__ __forceinline__ void gemm_phase(PG8_LAS unsigned char* lds, const Gemm g, const Sched& S, const Epi& E) {
;     ...
;             PG8_LDB(B0, 1, 0); PG8_LDB(B1, 1, 1); PG8_SCHED; PG8_LDA(At, 1, 0); PG8_STAGE(PG8_SA(0, 1), a2 + hstep, voffA);
;             PG8_WAIT_V(8); PG8_WAIT_L(0); PG8_BAR; PG8_MMA(0, 0, At, B0); PG8_MMA(0, 1, At, B1); PG8_BAR; PG8_SCHED;
;             PG8_LDA(At, 1, 1); PG8_STAGE(PG8_SB(1, 0), b3, voffB); PG8_STAGE(PG8_SB(1, 1), b3 + hstep, voffB); PG8_STAGE(PG8_SA(1, 0), a3, voffA);
;             PG8_WAIT_V(8); PG8_WAIT_L(0); PG8_BAR; PG8_MMA(1, 0, At, B0); PG8_MMA(1, 1, At, B1); PG8_BAR; PG8_SCHED;
;     ...
;         if constexpr (ALIGN_EPI) { if (wr == 0) PG8_BAR; }
	s_add_i32 s88, 0, 0x18000
	s_add_i32 s89, 0, 0x1c000
	ds_read_b128 v[142:145], v200 offset:32768
	ds_read_b128 v[146:149], v200 offset:33792
	ds_read_b128 v[150:153], v200 offset:34816
	ds_read_b128 v[154:157], v200 offset:35840
	ds_read_b128 v[164:167], v200 offset:49152
	ds_read_b128 v[168:171], v200 offset:50176
	ds_read_b128 v[172:175], v200 offset:51200
	ds_read_b128 v[176:179], v200 offset:52224
	s_add_u32 s52, s52, 0x80000
	s_addc_u32 s53, s53, 0
	s_mov_b32 m0, s56
	ds_read_b128 v[180:183], v141 offset:32768
	ds_read_b128 v[184:187], v141 offset:33792
	ds_read_b128 v[188:191], v141 offset:34816
	ds_read_b128 v[192:195], v141 offset:35840
	ds_read_b128 v[196:199], v141 offset:36864
	ds_read_b128 v[222:225], v141 offset:37888
	ds_read_b128 v[226:229], v141 offset:38912
	ds_read_b128 v[230:233], v141 offset:39936
	global_load_lds_dwordx4 v132, s[52:53]
	s_mov_b32 m0, s57
	s_nop 0
	global_load_lds_dwordx4 v130, s[52:53]
	s_waitcnt vmcnt(8)
	s_waitcnt lgkmcnt(0)
	s_barrier
	s_waitcnt lgkmcnt(0)
	v_mfma_f32_16x16x32_bf16 v[124:127], v[142:145], v[180:183], v[124:127]
	v_mfma_f32_16x16x32_bf16 v[120:123], v[150:153], v[180:183], v[120:123]
	v_mfma_f32_16x16x32_bf16 v[116:119], v[142:145], v[188:191], v[116:119]
	v_mfma_f32_16x16x32_bf16 v[112:115], v[150:153], v[188:191], v[112:115]
	v_mfma_f32_16x16x32_bf16 v[100:103], v[142:145], v[196:199], v[100:103]
	v_mfma_f32_16x16x32_bf16 v[96:99], v[150:153], v[196:199], v[96:99]
	v_mfma_f32_16x16x32_bf16 v[84:87], v[142:145], v[226:229], v[84:87]
	v_mfma_f32_16x16x32_bf16 v[80:83], v[150:153], v[226:229], v[80:83]
	v_mfma_f32_16x16x32_bf16 v[124:127], v[146:149], v[184:187], v[124:127]
	v_mfma_f32_16x16x32_bf16 v[120:123], v[154:157], v[184:187], v[120:123]
	v_mfma_f32_16x16x32_bf16 v[116:119], v[146:149], v[192:195], v[116:119]
	v_mfma_f32_16x16x32_bf16 v[112:115], v[154:157], v[192:195], v[112:115]
	v_mfma_f32_16x16x32_bf16 v[100:103], v[146:149], v[222:225], v[100:103]
	v_mfma_f32_16x16x32_bf16 v[96:99], v[154:157], v[222:225], v[96:99]
	v_mfma_f32_16x16x32_bf16 v[84:87], v[146:149], v[230:233], v[84:87]
	v_mfma_f32_16x16x32_bf16 v[80:83], v[154:157], v[230:233], v[80:83]
	v_mfma_f32_16x16x32_bf16 v[108:111], v[164:167], v[180:183], v[108:111]
	v_mfma_f32_16x16x32_bf16 v[104:107], v[172:175], v[180:183], v[104:107]
	v_mfma_f32_16x16x32_bf16 v[92:95], v[164:167], v[188:191], v[92:95]
	v_mfma_f32_16x16x32_bf16 v[88:91], v[172:175], v[188:191], v[88:91]
	v_mfma_f32_16x16x32_bf16 v[76:79], v[164:167], v[196:199], v[76:79]
	v_mfma_f32_16x16x32_bf16 v[72:75], v[172:175], v[196:199], v[72:75]
	v_mfma_f32_16x16x32_bf16 v[68:71], v[164:167], v[226:229], v[68:71]
	v_mfma_f32_16x16x32_bf16 v[64:67], v[172:175], v[226:229], v[64:67]
	v_mfma_f32_16x16x32_bf16 v[108:111], v[168:171], v[184:187], v[108:111]
	v_mfma_f32_16x16x32_bf16 v[104:107], v[176:179], v[184:187], v[104:107]
	v_mfma_f32_16x16x32_bf16 v[92:95], v[168:171], v[192:195], v[92:95]
	v_mfma_f32_16x16x32_bf16 v[88:91], v[176:179], v[192:195], v[88:91]
	v_mfma_f32_16x16x32_bf16 v[76:79], v[168:171], v[222:225], v[76:79]
	v_mfma_f32_16x16x32_bf16 v[72:75], v[176:179], v[222:225], v[72:75]
	v_mfma_f32_16x16x32_bf16 v[68:71], v[168:171], v[230:233], v[68:71]
	v_mfma_f32_16x16x32_bf16 v[64:67], v[176:179], v[230:233], v[64:67]
	s_barrier
	s_add_i32 s52, s88, s28
	s_mov_b32 m0, s52
	ds_read_b128 v[180:183], v141 offset:49152
	ds_read_b128 v[184:187], v141 offset:50176
	ds_read_b128 v[188:191], v141 offset:51200
	ds_read_b128 v[192:195], v141 offset:52224
	ds_read_b128 v[196:199], v141 offset:53248
	ds_read_b128 v[222:225], v141 offset:54272
	ds_read_b128 v[226:229], v141 offset:55296
	ds_read_b128 v[230:233], v141 offset:56320
	s_add_u32 s4, s4, 0x80
	s_addc_u32 s5, s5, 0
	global_load_lds_dwordx4 v160, s[4:5]
	s_add_i32 m0, s52, 0x2000
	s_add_i32 s52, s89, s28
	global_load_lds_dwordx4 v128, s[4:5]
	s_add_u32 s4, s4, 0x80000
	s_addc_u32 s5, s5, 0
	s_mov_b32 m0, s52
	s_nop 0
	global_load_lds_dwordx4 v160, s[4:5]
	s_add_i32 m0, s52, 0x2000
	s_nop 0
	global_load_lds_dwordx4 v128, s[4:5]
	s_mov_b32 m0, s24
	s_nop 0
	global_load_lds_dwordx4 v132, s[98:99]
	s_mov_b32 m0, s59
	s_nop 0
	global_load_lds_dwordx4 v130, s[98:99]
	s_waitcnt vmcnt(8)
	s_waitcnt lgkmcnt(0)
	s_barrier
	s_waitcnt lgkmcnt(0)
	v_mfma_f32_16x16x32_bf16 v[60:63], v[142:145], v[180:183], v[60:63]
	v_mfma_f32_16x16x32_bf16 v[56:59], v[150:153], v[180:183], v[56:59]
	v_mfma_f32_16x16x32_bf16 v[52:55], v[142:145], v[188:191], v[52:55]
	v_mfma_f32_16x16x32_bf16 v[48:51], v[150:153], v[188:191], v[48:51]
	v_mfma_f32_16x16x32_bf16 v[36:39], v[142:145], v[196:199], v[36:39]
	v_mfma_f32_16x16x32_bf16 v[32:35], v[150:153], v[196:199], v[32:35]
	v_mfma_f32_16x16x32_bf16 v[20:23], v[142:145], v[226:229], v[20:23]
	v_mfma_f32_16x16x32_bf16 v[16:19], v[150:153], v[226:229], v[16:19]
	v_mfma_f32_16x16x32_bf16 v[60:63], v[146:149], v[184:187], v[60:63]
	v_mfma_f32_16x16x32_bf16 v[56:59], v[154:157], v[184:187], v[56:59]
	v_mfma_f32_16x16x32_bf16 v[52:55], v[146:149], v[192:195], v[52:55]
	v_mfma_f32_16x16x32_bf16 v[48:51], v[154:157], v[192:195], v[48:51]
	v_mfma_f32_16x16x32_bf16 v[36:39], v[146:149], v[222:225], v[36:39]
	v_mfma_f32_16x16x32_bf16 v[32:35], v[154:157], v[222:225], v[32:35]
	v_mfma_f32_16x16x32_bf16 v[20:23], v[146:149], v[230:233], v[20:23]
	v_mfma_f32_16x16x32_bf16 v[16:19], v[154:157], v[230:233], v[16:19]
	v_mfma_f32_16x16x32_bf16 v[44:47], v[164:167], v[180:183], v[44:47]
	v_mfma_f32_16x16x32_bf16 v[40:43], v[172:175], v[180:183], v[40:43]
	v_mfma_f32_16x16x32_bf16 v[28:31], v[164:167], v[188:191], v[28:31]
	v_mfma_f32_16x16x32_bf16 v[24:27], v[172:175], v[188:191], v[24:27]
	v_mfma_f32_16x16x32_bf16 v[12:15], v[164:167], v[196:199], v[12:15]
	v_mfma_f32_16x16x32_bf16 v[8:11], v[172:175], v[196:199], v[8:11]
	v_mfma_f32_16x16x32_bf16 v[4:7], v[164:167], v[226:229], v[4:7]
	v_mfma_f32_16x16x32_bf16 v[0:3], v[172:175], v[226:229], v[0:3]
	v_mfma_f32_16x16x32_bf16 v[44:47], v[168:171], v[184:187], v[44:47]
	v_mfma_f32_16x16x32_bf16 v[40:43], v[176:179], v[184:187], v[40:43]
	v_mfma_f32_16x16x32_bf16 v[28:31], v[168:171], v[192:195], v[28:31]
	v_mfma_f32_16x16x32_bf16 v[24:27], v[176:179], v[192:195], v[24:27]
	v_mfma_f32_16x16x32_bf16 v[12:15], v[168:171], v[222:225], v[12:15]
	v_mfma_f32_16x16x32_bf16 v[8:11], v[176:179], v[222:225], v[8:11]
	v_mfma_f32_16x16x32_bf16 v[4:7], v[168:171], v[230:233], v[4:7]
	v_mfma_f32_16x16x32_bf16 v[0:3], v[176:179], v[230:233], v[0:3]
	s_barrier
	s_add_i32 s87, s87, 2
	s_add_u32 s80, s80, 0x100
	s_addc_u32 s81, s81, 0
	s_add_u32 s85, s85, 0x100
	s_addc_u32 s86, s86, 0
	s_cmp_gt_u32 s87, 29
	s_cbranch_scc0 .LBB0_25
	s_and_b64 vcc, exec, s[42:43]
	s_cbranch_vccz .LBB0_28
	s_barrier

; #define PG8_STAGE(bufoff, gbase, voff) do { _Pragma("unroll") for (int _i = 0; _i < 2; ++_i) \
;         __builtin_amdgcn_global_load_lds((const unsigned*)((const char*)(gbase) + (voff)[_i]), (PG8_LAS unsigned*)(lds + (bufoff) + ldsw + _i * 8192), 16, 0, 0); } while (0)
; #define PG8_LDA(dst, b, h) do { _Pragma("unroll") for (int m = 0; m < 4; ++m) _Pragma("unroll") for (int k = 0; k < 2; ++k) dst[m][k] = *(const PG8_LAS bf16x8*)(lds + PG8_SA(b, h) + aoff + m * 2048 + k * 1024); } while (0)
; #define PG8_LDB(dst, b, h) do { _Pragma("unroll") for (int n = 0; n < 2; ++n) _Pragma("unroll") for (int k = 0; k < 2; ++k) dst[n][k] = *(const PG8_LAS bf16x8*)(lds + PG8_SB(b, h) + boff + n * 2048 + k * 1024); } while (0)
; #define PG8_MMA(ai, bj, At, Bt) do { __builtin_amdgcn_s_setprio(1); _Pragma("unroll") for (int m = 0; m < 4; ++m) _Pragma("unroll") for (int n = 0; n < 2; ++n) _Pragma("unroll") for (int k = 0; k < 2; ++k) \
;         acc[ai][bj][m][n] = __builtin_amdgcn_mfma_f32_16x16x32_bf16(Bt[n][k], At[m][k], acc[ai][bj][m][n], 0, 0, 0); __builtin_amdgcn_s_setprio(0); } while (0)
; #define PG8_WAIT_V(n) asm volatile("s_waitcnt vmcnt(" #n ")" ::: "memory")
; #define PG8_WAIT_L(n) asm volatile("s_waitcnt lgkmcnt(" #n ")" ::: "memory")
; #define PG8_BAR __builtin_amdgcn_s_barrier()
; template <class Epi, class Sched, bool ALIGN_EPI = false, bool SP2 = false>
; __device__ __forceinline__ void gemm_phase(PG8_LAS unsigned char* lds, const Gemm g, const Sched& S, const Epi& E) {
;     ...
;             const char* a1 = cA + (size_t)(t + 1) * kstep;
;             const char* a2 = last ? nA : cA + (size_t)(t + 2) * kstep; const char* b2 = last ? nB : cB + (size_t)(t + 2) * kstep;
;             const char* a3 = a2 + kstep; const char* b3 = b2 + kstep;
;             if (last && has_next) S.a_ready(nxt);
;             if constexpr (SP2) {
;             PG8_LDB(B0, 0, 0); PG8_LDB(B1, 0, 1); PG8_SCHED; PG8_LDA(At, 0, 0); PG8_STAGE(PG8_SA(1, 1), a1 + hstep, voffA);
;             PG8_WAIT_V(8); PG8_WAIT_L(0); PG8_BAR; PG8_MMA(0, 0, At, B0); PG8_MMA(0, 1, At, B1); PG8_BAR; PG8_SCHED;
;             PG8_LDA(At, 0, 1); PG8_STAGE(PG8_SB(0, 0), b2, voffB); PG8_STAGE(PG8_SB(0, 1), b2 + hstep, voffB); PG8_STAGE(PG8_SA(0, 0), a2, voffA);
;             PG8_WAIT_V(8); PG8_WAIT_L(0); PG8_BAR; PG8_MMA(1, 0, At, B0); PG8_MMA(1, 1, At, B1); PG8_BAR; PG8_SCHED;
.LBB0_52:
	s_add_i32 s84, 0, 0x10000
	s_add_i32 s85, 0, 0x14000
	ds_read_b128 v[142:145], v200
	ds_read_b128 v[146:149], v200 offset:1024
	ds_read_b128 v[150:153], v200 offset:2048
	ds_read_b128 v[154:157], v200 offset:3072
	ds_read_b128 v[164:167], v200 offset:16384
	ds_read_b128 v[168:171], v200 offset:17408
	ds_read_b128 v[172:175], v200 offset:18432
	ds_read_b128 v[176:179], v200 offset:19456
	s_add_i32 m0, s28, 0xc000
	ds_read_b128 v[180:183], v141
	ds_read_b128 v[184:187], v141 offset:1024
	ds_read_b128 v[188:191], v141 offset:2048
	ds_read_b128 v[192:195], v141 offset:3072
	ds_read_b128 v[196:199], v141 offset:4096
	ds_read_b128 v[222:225], v141 offset:5120
	ds_read_b128 v[226:229], v141 offset:6144
	ds_read_b128 v[230:233], v141 offset:7168
	global_load_lds_dwordx4 v134, s[72:73]
	s_add_i32 m0, s28, 0xe000
	s_nop 0
	global_load_lds_dwordx4 v136, s[72:73]
	s_add_u32 s4, s72, 0x100
	s_addc_u32 s5, s73, 0
	s_cmpk_eq_i32 s83, 0x54
	s_cselect_b32 s57, s45, s5
	s_cselect_b32 s56, s44, s4
	s_cselect_b32 s53, s55, s82
	s_cselect_b32 s52, s54, s81
	s_waitcnt vmcnt(8)
	s_waitcnt lgkmcnt(0)
	s_barrier
	s_waitcnt lgkmcnt(0)
	v_mfma_f32_16x16x32_bf16 v[124:127], v[142:145], v[180:183], v[124:127]
	v_mfma_f32_16x16x32_bf16 v[120:123], v[150:153], v[180:183], v[120:123]
	v_mfma_f32_16x16x32_bf16 v[116:119], v[142:145], v[188:191], v[116:119]
	v_mfma_f32_16x16x32_bf16 v[112:115], v[150:153], v[188:191], v[112:115]
	v_mfma_f32_16x16x32_bf16 v[100:103], v[142:145], v[196:199], v[100:103]
	v_mfma_f32_16x16x32_bf16 v[96:99], v[150:153], v[196:199], v[96:99]
	v_mfma_f32_16x16x32_bf16 v[84:87], v[142:145], v[226:229], v[84:87]
	v_mfma_f32_16x16x32_bf16 v[80:83], v[150:153], v[226:229], v[80:83]
	v_mfma_f32_16x16x32_bf16 v[124:127], v[146:149], v[184:187], v[124:127]
	v_mfma_f32_16x16x32_bf16 v[120:123], v[154:157], v[184:187], v[120:123]
	v_mfma_f32_16x16x32_bf16 v[116:119], v[146:149], v[192:195], v[116:119]
	v_mfma_f32_16x16x32_bf16 v[112:115], v[154:157], v[192:195], v[112:115]
	v_mfma_f32_16x16x32_bf16 v[100:103], v[146:149], v[222:225], v[100:103]
	v_mfma_f32_16x16x32_bf16 v[96:99], v[154:157], v[222:225], v[96:99]
	v_mfma_f32_16x16x32_bf16 v[84:87], v[146:149], v[230:233], v[84:87]
	v_mfma_f32_16x16x32_bf16 v[80:83], v[154:157], v[230:233], v[80:83]
	v_mfma_f32_16x16x32_bf16 v[108:111], v[164:167], v[180:183], v[108:111]
	v_mfma_f32_16x16x32_bf16 v[104:107], v[172:175], v[180:183], v[104:107]
	v_mfma_f32_16x16x32_bf16 v[92:95], v[164:167], v[188:191], v[92:95]
	v_mfma_f32_16x16x32_bf16 v[88:91], v[172:175], v[188:191], v[88:91]
	v_mfma_f32_16x16x32_bf16 v[76:79], v[164:167], v[196:199], v[76:79]
	v_mfma_f32_16x16x32_bf16 v[72:75], v[172:175], v[196:199], v[72:75]
	v_mfma_f32_16x16x32_bf16 v[68:71], v[164:167], v[226:229], v[68:71]
	v_mfma_f32_16x16x32_bf16 v[64:67], v[172:175], v[226:229], v[64:67]
	v_mfma_f32_16x16x32_bf16 v[108:111], v[168:171], v[184:187], v[108:111]
	v_mfma_f32_16x16x32_bf16 v[104:107], v[176:179], v[184:187], v[104:107]
	v_mfma_f32_16x16x32_bf16 v[92:95], v[168:171], v[192:195], v[92:95]
	v_mfma_f32_16x16x32_bf16 v[88:91], v[176:179], v[192:195], v[88:91]
	v_mfma_f32_16x16x32_bf16 v[76:79], v[168:171], v[222:225], v[76:79]
	v_mfma_f32_16x16x32_bf16 v[72:75], v[176:179], v[222:225], v[72:75]
	v_mfma_f32_16x16x32_bf16 v[68:71], v[168:171], v[230:233], v[68:71]
	v_mfma_f32_16x16x32_bf16 v[64:67], v[176:179], v[230:233], v[64:67]
	s_barrier
	s_add_i32 s72, s84, s24
	s_mov_b32 m0, s72
	ds_read_b128 v[180:183], v141 offset:16384
	ds_read_b128 v[184:187], v141 offset:17408
	ds_read_b128 v[188:191], v141 offset:18432
	ds_read_b128 v[192:195], v141 offset:19456
	ds_read_b128 v[196:199], v141 offset:20480
	ds_read_b128 v[222:225], v141 offset:21504
	ds_read_b128 v[226:229], v141 offset:22528
	ds_read_b128 v[230:233], v141 offset:23552
	global_load_lds_dwordx4 v160, s[52:53]
	s_add_i32 m0, s72, 0x2000
	s_add_u32 s72, s52, 0x160000
	s_addc_u32 s73, s53, 0
	s_add_i32 s84, s85, s24
	global_load_lds_dwordx4 v128, s[52:53]
	s_mov_b32 m0, s84
	s_nop 0
	global_load_lds_dwordx4 v160, s[72:73]
	s_add_i32 m0, s84, 0x2000
	s_nop 0
	global_load_lds_dwordx4 v128, s[72:73]
	s_mov_b32 m0, s28
	s_nop 0
	global_load_lds_dwordx4 v132, s[56:57]
	s_mov_b32 m0, s29
	s_nop 0
	global_load_lds_dwordx4 v130, s[56:57]
	s_add_u32 s98, s56, 0x80
	s_addc_u32 s99, s57, 0
	s_waitcnt vmcnt(8)
	s_waitcnt lgkmcnt(0)
	s_barrier
	s_waitcnt lgkmcnt(0)
	v_mfma_f32_16x16x32_bf16 v[60:63], v[142:145], v[180:183], v[60:63]
	v_mfma_f32_16x16x32_bf16 v[56:59], v[150:153], v[180:183], v[56:59]
	v_mfma_f32_16x16x32_bf16 v[52:55], v[142:145], v[188:191], v[52:55]
	v_mfma_f32_16x16x32_bf16 v[48:51], v[150:153], v[188:191], v[48:51]
	v_mfma_f32_16x16x32_bf16 v[36:39], v[142:145], v[196:199], v[36:39]
	v_mfma_f32_16x16x32_bf16 v[32:35], v[150:153], v[196:199], v[32:35]
	v_mfma_f32_16x16x32_bf16 v[20:23], v[142:145], v[226:229], v[20:23]
	v_mfma_f32_16x16x32_bf16 v[16:19], v[150:153], v[226:229], v[16:19]
	v_mfma_f32_16x16x32_bf16 v[60:63], v[146:149], v[184:187], v[60:63]
	v_mfma_f32_16x16x32_bf16 v[56:59], v[154:157], v[184:187], v[56:59]
	v_mfma_f32_16x16x32_bf16 v[52:55], v[146:149], v[192:195], v[52:55]
	v_mfma_f32_16x16x32_bf16 v[48:51], v[154:157], v[192:195], v[48:51]
	v_mfma_f32_16x16x32_bf16 v[36:39], v[146:149], v[222:225], v[36:39]
	v_mfma_f32_16x16x32_bf16 v[32:35], v[154:157], v[222:225], v[32:35]
	v_mfma_f32_16x16x32_bf16 v[20:23], v[146:149], v[230:233], v[20:23]
	v_mfma_f32_16x16x32_bf16 v[16:19], v[154:157], v[230:233], v[16:19]
	v_mfma_f32_16x16x32_bf16 v[44:47], v[164:167], v[180:183], v[44:47]
	v_mfma_f32_16x16x32_bf16 v[40:43], v[172:175], v[180:183], v[40:43]
	v_mfma_f32_16x16x32_bf16 v[28:31], v[164:167], v[188:191], v[28:31]
	v_mfma_f32_16x16x32_bf16 v[24:27], v[172:175], v[188:191], v[24:27]
	v_mfma_f32_16x16x32_bf16 v[12:15], v[164:167], v[196:199], v[12:15]
	v_mfma_f32_16x16x32_bf16 v[8:11], v[172:175], v[196:199], v[8:11]
	v_mfma_f32_16x16x32_bf16 v[4:7], v[164:167], v[226:229], v[4:7]
	v_mfma_f32_16x16x32_bf16 v[0:3], v[172:175], v[226:229], v[0:3]
	v_mfma_f32_16x16x32_bf16 v[44:47], v[168:171], v[184:187], v[44:47]
	v_mfma_f32_16x16x32_bf16 v[40:43], v[176:179], v[184:187], v[40:43]
	v_mfma_f32_16x16x32_bf16 v[28:31], v[168:171], v[192:195], v[28:31]
	v_mfma_f32_16x16x32_bf16 v[24:27], v[176:179], v[192:195], v[24:27]
	v_mfma_f32_16x16x32_bf16 v[12:15], v[168:171], v[222:225], v[12:15]
	v_mfma_f32_16x16x32_bf16 v[8:11], v[176:179], v[222:225], v[8:11]
	v_mfma_f32_16x16x32_bf16 v[4:7], v[168:171], v[230:233], v[4:7]
	v_mfma_f32_16x16x32_bf16 v[0:3], v[176:179], v[230:233], v[0:3]
	s_barrier
; #define PG8_STAGE(bufoff, gbase, voff) do { _Pragma("unroll") for (int _i = 0; _i < 2; ++_i) \
;         __builtin_amdgcn_global_load_lds((const unsigned*)((const char*)(gbase) + (voff)[_i]), (PG8_LAS unsigned*)(lds + (bufoff) + ldsw + _i * 8192), 16, 0, 0); } while (0)
; #define PG8_LDA(dst, b, h) do { _Pragma("unroll") for (int m = 0; m < 4; ++m) _Pragma("unroll") for (int k = 0; k < 2; ++k) dst[m][k] = *(const PG8_LAS bf16x8*)(lds + PG8_SA(b, h) + aoff + m * 2048 + k * 1024); } while (0)
; #define PG8_LDB(dst, b, h) do { _Pragma("unroll") for (int n = 0; n < 2; ++n) _Pragma("unroll") for (int k = 0; k < 2; ++k) dst[n][k] = *(const PG8_LAS bf16x8*)(lds + PG8_SB(b, h) + boff + n * 2048 + k * 1024); } while (0)
; #define PG8_MMA(ai, bj, At, Bt) do { __builtin_amdgcn_s_setprio(1); _Pragma("unroll") for (int m = 0; m < 4; ++m) _Pragma("unroll") for (int n = 0; n < 2; ++n) _Pragma("unroll") for (int k = 0; k < 2; ++k) \
;         acc[ai][bj][m][n] = __builtin_amdgcn_mfma_f32_16x16x32_bf16(Bt[n][k], At[m][k], acc[ai][bj][m][n], 0, 0, 0); __builtin_amdgcn_s_setprio(0); } while (0)
; #define PG8_WAIT_V(n) asm volatile("s_waitcnt vmcnt(" #n ")" ::: "memory")
; #define PG8_WAIT_L(n) asm volatile("s_waitcnt lgkmcnt(" #n ")" ::: "memory")
; #define PG8_BAR __builtin_amdgcn_s_barrier()
; #define PG8_SCHED __builtin_amdgcn_sched_barrier(0)
; template <class Epi, class Sched, bool ALIGN_EPI = false, bool SP2 = false>
; __device__ __forceinline__ void gemm_phase(PG8_LAS unsigned char* lds, const Gemm g, const Sched& S, const Epi& E) {
;     ...
;             PG8_LDB(B0, 1, 0); PG8_LDB(B1, 1, 1); PG8_SCHED; PG8_LDA(At, 1, 0); PG8_STAGE(PG8_SA(0, 1), a2 + hstep, voffA);
;             PG8_WAIT_V(8); PG8_WAIT_L(0); PG8_BAR; PG8_MMA(0, 0, At, B0); PG8_MMA(0, 1, At, B1); PG8_BAR; PG8_SCHED;
;             PG8_LDA(At, 1, 1); PG8_STAGE(PG8_SB(1, 0), b3, voffB); PG8_STAGE(PG8_SB(1, 1), b3 + hstep, voffB); PG8_STAGE(PG8_SA(1, 0), a3, voffA);
;             PG8_WAIT_V(8); PG8_WAIT_L(0); PG8_BAR; PG8_MMA(1, 0, At, B0); PG8_MMA(1, 1, At, B1); PG8_BAR; PG8_SCHED;
;     ...
;         if constexpr (ALIGN_EPI) { if (wr == 0) PG8_BAR; }
	s_add_i32 s72, 0, 0x18000
	s_add_i32 s73, 0, 0x1c000
	ds_read_b128 v[142:145], v200 offset:32768
	ds_read_b128 v[146:149], v200 offset:33792
	ds_read_b128 v[150:153], v200 offset:34816
	ds_read_b128 v[154:157], v200 offset:35840
	ds_read_b128 v[164:167], v200 offset:49152
	ds_read_b128 v[168:171], v200 offset:50176
	ds_read_b128 v[172:175], v200 offset:51200
	ds_read_b128 v[176:179], v200 offset:52224
	s_add_u32 s56, s56, 0x160000
	s_addc_u32 s57, s57, 0
	s_mov_b32 m0, s59
	ds_read_b128 v[180:183], v141 offset:32768
	ds_read_b128 v[184:187], v141 offset:33792
	ds_read_b128 v[188:191], v141 offset:34816
	ds_read_b128 v[192:195], v141 offset:35840
	ds_read_b128 v[196:199], v141 offset:36864
	ds_read_b128 v[222:225], v141 offset:37888
	ds_read_b128 v[226:229], v141 offset:38912
	ds_read_b128 v[230:233], v141 offset:39936
	global_load_lds_dwordx4 v132, s[56:57]
	s_mov_b32 m0, s63
	s_nop 0
	global_load_lds_dwordx4 v130, s[56:57]
	s_waitcnt vmcnt(8)
	s_waitcnt lgkmcnt(0)
	s_barrier
	s_waitcnt lgkmcnt(0)
	v_mfma_f32_16x16x32_bf16 v[124:127], v[142:145], v[180:183], v[124:127]
	v_mfma_f32_16x16x32_bf16 v[120:123], v[150:153], v[180:183], v[120:123]
	v_mfma_f32_16x16x32_bf16 v[116:119], v[142:145], v[188:191], v[116:119]
	v_mfma_f32_16x16x32_bf16 v[112:115], v[150:153], v[188:191], v[112:115]
	v_mfma_f32_16x16x32_bf16 v[100:103], v[142:145], v[196:199], v[100:103]
	v_mfma_f32_16x16x32_bf16 v[96:99], v[150:153], v[196:199], v[96:99]
	v_mfma_f32_16x16x32_bf16 v[84:87], v[142:145], v[226:229], v[84:87]
	v_mfma_f32_16x16x32_bf16 v[80:83], v[150:153], v[226:229], v[80:83]
	v_mfma_f32_16x16x32_bf16 v[124:127], v[146:149], v[184:187], v[124:127]
	v_mfma_f32_16x16x32_bf16 v[120:123], v[154:157], v[184:187], v[120:123]
	v_mfma_f32_16x16x32_bf16 v[116:119], v[146:149], v[192:195], v[116:119]
	v_mfma_f32_16x16x32_bf16 v[112:115], v[154:157], v[192:195], v[112:115]
	v_mfma_f32_16x16x32_bf16 v[100:103], v[146:149], v[222:225], v[100:103]
	v_mfma_f32_16x16x32_bf16 v[96:99], v[154:157], v[222:225], v[96:99]
	v_mfma_f32_16x16x32_bf16 v[84:87], v[146:149], v[230:233], v[84:87]
	v_mfma_f32_16x16x32_bf16 v[80:83], v[154:157], v[230:233], v[80:83]
	v_mfma_f32_16x16x32_bf16 v[108:111], v[164:167], v[180:183], v[108:111]
	v_mfma_f32_16x16x32_bf16 v[104:107], v[172:175], v[180:183], v[104:107]
	v_mfma_f32_16x16x32_bf16 v[92:95], v[164:167], v[188:191], v[92:95]
	v_mfma_f32_16x16x32_bf16 v[88:91], v[172:175], v[188:191], v[88:91]
	v_mfma_f32_16x16x32_bf16 v[76:79], v[164:167], v[196:199], v[76:79]
	v_mfma_f32_16x16x32_bf16 v[72:75], v[172:175], v[196:199], v[72:75]
	v_mfma_f32_16x16x32_bf16 v[68:71], v[164:167], v[226:229], v[68:71]
	v_mfma_f32_16x16x32_bf16 v[64:67], v[172:175], v[226:229], v[64:67]
	v_mfma_f32_16x16x32_bf16 v[108:111], v[168:171], v[184:187], v[108:111]
	v_mfma_f32_16x16x32_bf16 v[104:107], v[176:179], v[184:187], v[104:107]
	v_mfma_f32_16x16x32_bf16 v[92:95], v[168:171], v[192:195], v[92:95]
	v_mfma_f32_16x16x32_bf16 v[88:91], v[176:179], v[192:195], v[88:91]
	v_mfma_f32_16x16x32_bf16 v[76:79], v[168:171], v[222:225], v[76:79]
	v_mfma_f32_16x16x32_bf16 v[72:75], v[176:179], v[222:225], v[72:75]
	v_mfma_f32_16x16x32_bf16 v[68:71], v[168:171], v[230:233], v[68:71]
	v_mfma_f32_16x16x32_bf16 v[64:67], v[176:179], v[230:233], v[64:67]
	s_barrier
	s_add_i32 s56, s72, s24
	s_mov_b32 m0, s56
	ds_read_b128 v[180:183], v141 offset:49152
	ds_read_b128 v[184:187], v141 offset:50176
	ds_read_b128 v[188:191], v141 offset:51200
	ds_read_b128 v[192:195], v141 offset:52224
	ds_read_b128 v[196:199], v141 offset:53248
	ds_read_b128 v[222:225], v141 offset:54272
	ds_read_b128 v[226:229], v141 offset:55296
	ds_read_b128 v[230:233], v141 offset:56320
	s_add_u32 s52, s52, 0x80
	s_addc_u32 s53, s53, 0
	global_load_lds_dwordx4 v160, s[52:53]
	s_add_i32 m0, s56, 0x2000
	s_add_i32 s56, s73, s24
	global_load_lds_dwordx4 v128, s[52:53]
	s_add_u32 s52, s52, 0x160000
	s_addc_u32 s53, s53, 0
	s_mov_b32 m0, s56
	s_nop 0
	global_load_lds_dwordx4 v160, s[52:53]
	s_add_i32 m0, s56, 0x2000
	s_nop 0
	global_load_lds_dwordx4 v128, s[52:53]
	s_mov_b32 m0, s74
	s_nop 0
	global_load_lds_dwordx4 v132, s[98:99]
	s_mov_b32 m0, s75
	s_nop 0
	global_load_lds_dwordx4 v130, s[98:99]
	s_waitcnt vmcnt(8)
	s_waitcnt lgkmcnt(0)
	s_barrier
	s_waitcnt lgkmcnt(0)
	v_mfma_f32_16x16x32_bf16 v[60:63], v[142:145], v[180:183], v[60:63]
	v_mfma_f32_16x16x32_bf16 v[56:59], v[150:153], v[180:183], v[56:59]
	v_mfma_f32_16x16x32_bf16 v[52:55], v[142:145], v[188:191], v[52:55]
	v_mfma_f32_16x16x32_bf16 v[48:51], v[150:153], v[188:191], v[48:51]
	v_mfma_f32_16x16x32_bf16 v[36:39], v[142:145], v[196:199], v[36:39]
	v_mfma_f32_16x16x32_bf16 v[32:35], v[150:153], v[196:199], v[32:35]
	v_mfma_f32_16x16x32_bf16 v[20:23], v[142:145], v[226:229], v[20:23]
	v_mfma_f32_16x16x32_bf16 v[16:19], v[150:153], v[226:229], v[16:19]
	v_mfma_f32_16x16x32_bf16 v[60:63], v[146:149], v[184:187], v[60:63]
	v_mfma_f32_16x16x32_bf16 v[56:59], v[154:157], v[184:187], v[56:59]
	v_mfma_f32_16x16x32_bf16 v[52:55], v[146:149], v[192:195], v[52:55]
	v_mfma_f32_16x16x32_bf16 v[48:51], v[154:157], v[192:195], v[48:51]
	v_mfma_f32_16x16x32_bf16 v[36:39], v[146:149], v[222:225], v[36:39]
	v_mfma_f32_16x16x32_bf16 v[32:35], v[154:157], v[222:225], v[32:35]
	v_mfma_f32_16x16x32_bf16 v[20:23], v[146:149], v[230:233], v[20:23]
	v_mfma_f32_16x16x32_bf16 v[16:19], v[154:157], v[230:233], v[16:19]
	v_mfma_f32_16x16x32_bf16 v[44:47], v[164:167], v[180:183], v[44:47]
	v_mfma_f32_16x16x32_bf16 v[40:43], v[172:175], v[180:183], v[40:43]
	v_mfma_f32_16x16x32_bf16 v[28:31], v[164:167], v[188:191], v[28:31]
	v_mfma_f32_16x16x32_bf16 v[24:27], v[172:175], v[188:191], v[24:27]
	v_mfma_f32_16x16x32_bf16 v[12:15], v[164:167], v[196:199], v[12:15]
	v_mfma_f32_16x16x32_bf16 v[8:11], v[172:175], v[196:199], v[8:11]
	v_mfma_f32_16x16x32_bf16 v[4:7], v[164:167], v[226:229], v[4:7]
	v_mfma_f32_16x16x32_bf16 v[0:3], v[172:175], v[226:229], v[0:3]
	v_mfma_f32_16x16x32_bf16 v[44:47], v[168:171], v[184:187], v[44:47]
	v_mfma_f32_16x16x32_bf16 v[40:43], v[176:179], v[184:187], v[40:43]
	v_mfma_f32_16x16x32_bf16 v[28:31], v[168:171], v[192:195], v[28:31]
	v_mfma_f32_16x16x32_bf16 v[24:27], v[176:179], v[192:195], v[24:27]
	v_mfma_f32_16x16x32_bf16 v[12:15], v[168:171], v[222:225], v[12:15]
	v_mfma_f32_16x16x32_bf16 v[8:11], v[176:179], v[222:225], v[8:11]
	v_mfma_f32_16x16x32_bf16 v[4:7], v[168:171], v[230:233], v[4:7]
	v_mfma_f32_16x16x32_bf16 v[0:3], v[176:179], v[230:233], v[0:3]
	s_barrier
	s_add_i32 s83, s83, 2
	s_add_u32 s81, s81, 0x100
	s_addc_u32 s82, s82, 0
	s_cmpk_gt_u32 s83, 0x55
	s_mov_b64 s[72:73], s[4:5]
	s_cbranch_scc0 .LBB0_52
	s_and_b64 vcc, exec, s[42:43]
	s_cbranch_vccz .LBB0_55
	s_barrier

; #define PG8_STAGE(bufoff, gbase, voff) do { _Pragma("unroll") for (int _i = 0; _i < 2; ++_i) \
;         __builtin_amdgcn_global_load_lds((const unsigned*)((const char*)(gbase) + (voff)[_i]), (PG8_LAS unsigned*)(lds + (bufoff) + ldsw + _i * 8192), 16, 0, 0); } while (0)
; #define PG8_LDA(dst, b, h) do { _Pragma("unroll") for (int m = 0; m < 4; ++m) _Pragma("unroll") for (int k = 0; k < 2; ++k) dst[m][k] = *(const PG8_LAS bf16x8*)(lds + PG8_SA(b, h) + aoff + m * 2048 + k * 1024); } while (0)
; #define PG8_LDB(dst, b, h) do { _Pragma("unroll") for (int n = 0; n < 2; ++n) _Pragma("unroll") for (int k = 0; k < 2; ++k) dst[n][k] = *(const PG8_LAS bf16x8*)(lds + PG8_SB(b, h) + boff + n * 2048 + k * 1024); } while (0)
; #define PG8_MMA(ai, bj, At, Bt) do { __builtin_amdgcn_s_setprio(1); _Pragma("unroll") for (int m = 0; m < 4; ++m) _Pragma("unroll") for (int n = 0; n < 2; ++n) _Pragma("unroll") for (int k = 0; k < 2; ++k) \
;         acc[ai][bj][m][n] = __builtin_amdgcn_mfma_f32_16x16x32_bf16(Bt[n][k], At[m][k], acc[ai][bj][m][n], 0, 0, 0); __builtin_amdgcn_s_setprio(0); } while (0)
; #define PG8_WAIT_V(n) asm volatile("s_waitcnt vmcnt(" #n ")" ::: "memory")
; #define PG8_WAIT_L(n) asm volatile("s_waitcnt lgkmcnt(" #n ")" ::: "memory")
; #define PG8_BAR __builtin_amdgcn_s_barrier()
; template <class Epi, class Sched, bool ALIGN_EPI = false, bool SP2 = false>
; __device__ __forceinline__ void gemm_phase(PG8_LAS unsigned char* lds, const Gemm g, const Sched& S, const Epi& E) {
;     ...
;             const char* a1 = cA + (size_t)(t + 1) * kstep;
;             const char* a2 = last ? nA : cA + (size_t)(t + 2) * kstep; const char* b2 = last ? nB : cB + (size_t)(t + 2) * kstep;
;             const char* a3 = a2 + kstep; const char* b3 = b2 + kstep;
;             if (last && has_next) S.a_ready(nxt);
;             if constexpr (SP2) {
;             PG8_LDB(B0, 0, 0); PG8_LDB(B1, 0, 1); PG8_SCHED; PG8_LDA(At, 0, 0); PG8_STAGE(PG8_SA(1, 1), a1 + hstep, voffA);
;             PG8_WAIT_V(8); PG8_WAIT_L(0); PG8_BAR; PG8_MMA(0, 0, At, B0); PG8_MMA(0, 1, At, B1); PG8_BAR; PG8_SCHED;
;             PG8_LDA(At, 0, 1); PG8_STAGE(PG8_SB(0, 0), b2, voffB); PG8_STAGE(PG8_SB(0, 1), b2 + hstep, voffB); PG8_STAGE(PG8_SA(0, 0), a2, voffA);
;             PG8_WAIT_V(8); PG8_WAIT_L(0); PG8_BAR; PG8_MMA(1, 0, At, B0); PG8_MMA(1, 1, At, B1); PG8_BAR; PG8_SCHED;
.LBB0_86:
	s_add_i32 s88, 0, 0x10000
	s_add_i32 s90, 0, 0x14000
	ds_read_b128 v[140:143], v200
	ds_read_b128 v[150:153], v200 offset:1024
	ds_read_b128 v[154:157], v200 offset:2048
	ds_read_b128 v[164:167], v200 offset:3072
	ds_read_b128 v[168:171], v200 offset:16384
	ds_read_b128 v[172:175], v200 offset:17408
	ds_read_b128 v[176:179], v200 offset:18432
	ds_read_b128 v[180:183], v200 offset:19456
	s_add_i32 m0, s63, 0xc000
	ds_read_b128 v[184:187], v149
	ds_read_b128 v[188:191], v149 offset:1024
	ds_read_b128 v[192:195], v149 offset:2048
	ds_read_b128 v[196:199], v149 offset:3072
	ds_read_b128 v[222:225], v149 offset:4096
	ds_read_b128 v[226:229], v149 offset:5120
	ds_read_b128 v[230:233], v149 offset:6144
	ds_read_b128 v[234:237], v149 offset:7168
	global_load_lds_dwordx4 v136, s[82:83]
	s_add_i32 m0, s63, 0xe000
	s_nop 0
	global_load_lds_dwordx4 v138, s[82:83]
	s_add_u32 s4, s82, 0xfffc0080
	s_addc_u32 s5, s83, -1
	s_cmp_eq_u32 s87, 12
	s_cselect_b32 s53, s7, s5
	s_cselect_b32 s52, s15, s4
	s_cselect_b32 s5, s24, s43
	s_cselect_b32 s4, s28, s29
	s_waitcnt vmcnt(8)
	s_waitcnt lgkmcnt(0)
	s_barrier
	s_waitcnt lgkmcnt(0)
	v_mfma_f32_16x16x32_bf16 v[124:127], v[140:143], v[184:187], v[124:127]
	v_mfma_f32_16x16x32_bf16 v[120:123], v[154:157], v[184:187], v[120:123]
	v_mfma_f32_16x16x32_bf16 v[108:111], v[140:143], v[192:195], v[108:111]
	v_mfma_f32_16x16x32_bf16 v[104:107], v[154:157], v[192:195], v[104:107]
	v_mfma_f32_16x16x32_bf16 v[92:95], v[140:143], v[222:225], v[92:95]
	v_mfma_f32_16x16x32_bf16 v[88:91], v[154:157], v[222:225], v[88:91]
	v_mfma_f32_16x16x32_bf16 v[76:79], v[140:143], v[230:233], v[76:79]
	v_mfma_f32_16x16x32_bf16 v[72:75], v[154:157], v[230:233], v[72:75]
	v_mfma_f32_16x16x32_bf16 v[124:127], v[150:153], v[188:191], v[124:127]
	v_mfma_f32_16x16x32_bf16 v[120:123], v[164:167], v[188:191], v[120:123]
	v_mfma_f32_16x16x32_bf16 v[108:111], v[150:153], v[196:199], v[108:111]
	v_mfma_f32_16x16x32_bf16 v[104:107], v[164:167], v[196:199], v[104:107]
	v_mfma_f32_16x16x32_bf16 v[92:95], v[150:153], v[226:229], v[92:95]
	v_mfma_f32_16x16x32_bf16 v[88:91], v[164:167], v[226:229], v[88:91]
	v_mfma_f32_16x16x32_bf16 v[76:79], v[150:153], v[234:237], v[76:79]
	v_mfma_f32_16x16x32_bf16 v[72:75], v[164:167], v[234:237], v[72:75]
	v_mfma_f32_16x16x32_bf16 v[116:119], v[168:171], v[184:187], v[116:119]
	v_mfma_f32_16x16x32_bf16 v[112:115], v[176:179], v[184:187], v[112:115]
	v_mfma_f32_16x16x32_bf16 v[100:103], v[168:171], v[192:195], v[100:103]
	v_mfma_f32_16x16x32_bf16 v[96:99], v[176:179], v[192:195], v[96:99]
	v_mfma_f32_16x16x32_bf16 v[84:87], v[168:171], v[222:225], v[84:87]
	v_mfma_f32_16x16x32_bf16 v[80:83], v[176:179], v[222:225], v[80:83]
	v_mfma_f32_16x16x32_bf16 v[68:71], v[168:171], v[230:233], v[68:71]
	v_mfma_f32_16x16x32_bf16 v[64:67], v[176:179], v[230:233], v[64:67]
	v_mfma_f32_16x16x32_bf16 v[116:119], v[172:175], v[188:191], v[116:119]
	v_mfma_f32_16x16x32_bf16 v[112:115], v[180:183], v[188:191], v[112:115]
	v_mfma_f32_16x16x32_bf16 v[100:103], v[172:175], v[196:199], v[100:103]
	v_mfma_f32_16x16x32_bf16 v[96:99], v[180:183], v[196:199], v[96:99]
	v_mfma_f32_16x16x32_bf16 v[84:87], v[172:175], v[226:229], v[84:87]
	v_mfma_f32_16x16x32_bf16 v[80:83], v[180:183], v[226:229], v[80:83]
	v_mfma_f32_16x16x32_bf16 v[68:71], v[172:175], v[234:237], v[68:71]
	v_mfma_f32_16x16x32_bf16 v[64:67], v[180:183], v[234:237], v[64:67]
	s_barrier
	s_add_i32 s88, s88, s59
	s_mov_b32 m0, s88
	ds_read_b128 v[184:187], v149 offset:16384
	ds_read_b128 v[188:191], v149 offset:17408
	ds_read_b128 v[192:195], v149 offset:18432
	ds_read_b128 v[196:199], v149 offset:19456
	ds_read_b128 v[222:225], v149 offset:20480
	ds_read_b128 v[226:229], v149 offset:21504
	ds_read_b128 v[230:233], v149 offset:22528
	ds_read_b128 v[234:237], v149 offset:23552
	global_load_lds_dwordx4 v130, s[4:5]
	s_add_i32 m0, s88, 0x2000
	s_add_u32 s88, s4, 0x40000
	s_addc_u32 s89, s5, 0
	s_add_i32 s90, s90, s59
	global_load_lds_dwordx4 v134, s[4:5]
	s_mov_b32 m0, s90
	s_nop 0
	global_load_lds_dwordx4 v130, s[88:89]
	s_add_i32 m0, s90, 0x2000
	s_nop 0
	global_load_lds_dwordx4 v134, s[88:89]
	s_mov_b32 m0, s63
	s_nop 0
	global_load_lds_dwordx4 v128, s[52:53]
	s_mov_b32 m0, s74
	s_nop 0
	global_load_lds_dwordx4 v132, s[52:53]
	s_add_u32 s98, s52, 0x80
	s_addc_u32 s99, s53, 0
	s_waitcnt vmcnt(8)
	s_waitcnt lgkmcnt(0)
	s_barrier
	s_waitcnt lgkmcnt(0)
	v_mfma_f32_16x16x32_bf16 v[60:63], v[140:143], v[184:187], v[60:63]
	v_mfma_f32_16x16x32_bf16 v[56:59], v[154:157], v[184:187], v[56:59]
	v_mfma_f32_16x16x32_bf16 v[44:47], v[140:143], v[192:195], v[44:47]
	v_mfma_f32_16x16x32_bf16 v[40:43], v[154:157], v[192:195], v[40:43]
	v_mfma_f32_16x16x32_bf16 v[28:31], v[140:143], v[222:225], v[28:31]
	v_mfma_f32_16x16x32_bf16 v[24:27], v[154:157], v[222:225], v[24:27]
	v_mfma_f32_16x16x32_bf16 v[12:15], v[140:143], v[230:233], v[12:15]
	v_mfma_f32_16x16x32_bf16 v[8:11], v[154:157], v[230:233], v[8:11]
	v_mfma_f32_16x16x32_bf16 v[60:63], v[150:153], v[188:191], v[60:63]
	v_mfma_f32_16x16x32_bf16 v[56:59], v[164:167], v[188:191], v[56:59]
	v_mfma_f32_16x16x32_bf16 v[44:47], v[150:153], v[196:199], v[44:47]
	v_mfma_f32_16x16x32_bf16 v[40:43], v[164:167], v[196:199], v[40:43]
	v_mfma_f32_16x16x32_bf16 v[28:31], v[150:153], v[226:229], v[28:31]
	v_mfma_f32_16x16x32_bf16 v[24:27], v[164:167], v[226:229], v[24:27]
	v_mfma_f32_16x16x32_bf16 v[12:15], v[150:153], v[234:237], v[12:15]
	v_mfma_f32_16x16x32_bf16 v[8:11], v[164:167], v[234:237], v[8:11]
	v_mfma_f32_16x16x32_bf16 v[52:55], v[168:171], v[184:187], v[52:55]
	v_mfma_f32_16x16x32_bf16 v[48:51], v[176:179], v[184:187], v[48:51]
	v_mfma_f32_16x16x32_bf16 v[36:39], v[168:171], v[192:195], v[36:39]
	v_mfma_f32_16x16x32_bf16 v[32:35], v[176:179], v[192:195], v[32:35]
	v_mfma_f32_16x16x32_bf16 v[20:23], v[168:171], v[222:225], v[20:23]
	v_mfma_f32_16x16x32_bf16 v[16:19], v[176:179], v[222:225], v[16:19]
	v_mfma_f32_16x16x32_bf16 v[4:7], v[168:171], v[230:233], v[4:7]
	v_mfma_f32_16x16x32_bf16 v[0:3], v[176:179], v[230:233], v[0:3]
	v_mfma_f32_16x16x32_bf16 v[52:55], v[172:175], v[188:191], v[52:55]
	v_mfma_f32_16x16x32_bf16 v[48:51], v[180:183], v[188:191], v[48:51]
	v_mfma_f32_16x16x32_bf16 v[36:39], v[172:175], v[196:199], v[36:39]
	v_mfma_f32_16x16x32_bf16 v[32:35], v[180:183], v[196:199], v[32:35]
	v_mfma_f32_16x16x32_bf16 v[20:23], v[172:175], v[226:229], v[20:23]
	v_mfma_f32_16x16x32_bf16 v[16:19], v[180:183], v[226:229], v[16:19]
	v_mfma_f32_16x16x32_bf16 v[4:7], v[172:175], v[234:237], v[4:7]
	v_mfma_f32_16x16x32_bf16 v[0:3], v[180:183], v[234:237], v[0:3]
	s_barrier
; #define PG8_STAGE(bufoff, gbase, voff) do { _Pragma("unroll") for (int _i = 0; _i < 2; ++_i) \
;         __builtin_amdgcn_global_load_lds((const unsigned*)((const char*)(gbase) + (voff)[_i]), (PG8_LAS unsigned*)(lds + (bufoff) + ldsw + _i * 8192), 16, 0, 0); } while (0)
; #define PG8_LDA(dst, b, h) do { _Pragma("unroll") for (int m = 0; m < 4; ++m) _Pragma("unroll") for (int k = 0; k < 2; ++k) dst[m][k] = *(const PG8_LAS bf16x8*)(lds + PG8_SA(b, h) + aoff + m * 2048 + k * 1024); } while (0)
; #define PG8_LDB(dst, b, h) do { _Pragma("unroll") for (int n = 0; n < 2; ++n) _Pragma("unroll") for (int k = 0; k < 2; ++k) dst[n][k] = *(const PG8_LAS bf16x8*)(lds + PG8_SB(b, h) + boff + n * 2048 + k * 1024); } while (0)
; #define PG8_MMA(ai, bj, At, Bt) do { __builtin_amdgcn_s_setprio(1); _Pragma("unroll") for (int m = 0; m < 4; ++m) _Pragma("unroll") for (int n = 0; n < 2; ++n) _Pragma("unroll") for (int k = 0; k < 2; ++k) \
;         acc[ai][bj][m][n] = __builtin_amdgcn_mfma_f32_16x16x32_bf16(Bt[n][k], At[m][k], acc[ai][bj][m][n], 0, 0, 0); __builtin_amdgcn_s_setprio(0); } while (0)
; #define PG8_WAIT_V(n) asm volatile("s_waitcnt vmcnt(" #n ")" ::: "memory")
; #define PG8_WAIT_L(n) asm volatile("s_waitcnt lgkmcnt(" #n ")" ::: "memory")
; #define PG8_BAR __builtin_amdgcn_s_barrier()
; #define PG8_SCHED __builtin_amdgcn_sched_barrier(0)
; template <class Epi, class Sched, bool ALIGN_EPI = false, bool SP2 = false>
; __device__ __forceinline__ void gemm_phase(PG8_LAS unsigned char* lds, const Gemm g, const Sched& S, const Epi& E) {
;     ...
;             PG8_LDB(B0, 1, 0); PG8_LDB(B1, 1, 1); PG8_SCHED; PG8_LDA(At, 1, 0); PG8_STAGE(PG8_SA(0, 1), a2 + hstep, voffA);
;             PG8_WAIT_V(8); PG8_WAIT_L(0); PG8_BAR; PG8_MMA(0, 0, At, B0); PG8_MMA(0, 1, At, B1); PG8_BAR; PG8_SCHED;
;             PG8_LDA(At, 1, 1); PG8_STAGE(PG8_SB(1, 0), b3, voffB); PG8_STAGE(PG8_SB(1, 1), b3 + hstep, voffB); PG8_STAGE(PG8_SA(1, 0), a3, voffA);
;             PG8_WAIT_V(8); PG8_WAIT_L(0); PG8_BAR; PG8_MMA(1, 0, At, B0); PG8_MMA(1, 1, At, B1); PG8_BAR; PG8_SCHED;
;     ...
;         if constexpr (ALIGN_EPI) { if (wr == 0) PG8_BAR; }
	s_add_i32 s88, 0, 0x18000
	s_add_i32 s89, 0, 0x1c000
	ds_read_b128 v[140:143], v200 offset:32768
	ds_read_b128 v[150:153], v200 offset:33792
	ds_read_b128 v[154:157], v200 offset:34816
	ds_read_b128 v[164:167], v200 offset:35840
	ds_read_b128 v[168:171], v200 offset:49152
	ds_read_b128 v[172:175], v200 offset:50176
	ds_read_b128 v[176:179], v200 offset:51200
	ds_read_b128 v[180:183], v200 offset:52224
	s_add_u32 s52, s52, 0x40000
	s_addc_u32 s53, s53, 0
	s_mov_b32 m0, s75
	ds_read_b128 v[184:187], v149 offset:32768
	ds_read_b128 v[188:191], v149 offset:33792
	ds_read_b128 v[192:195], v149 offset:34816
	ds_read_b128 v[196:199], v149 offset:35840
	ds_read_b128 v[222:225], v149 offset:36864
	ds_read_b128 v[226:229], v149 offset:37888
	ds_read_b128 v[230:233], v149 offset:38912
	ds_read_b128 v[234:237], v149 offset:39936
	global_load_lds_dwordx4 v128, s[52:53]
	s_mov_b32 m0, s81
	s_nop 0
	global_load_lds_dwordx4 v132, s[52:53]
	s_waitcnt vmcnt(8)
	s_waitcnt lgkmcnt(0)
	s_barrier
	s_waitcnt lgkmcnt(0)
	v_mfma_f32_16x16x32_bf16 v[124:127], v[140:143], v[184:187], v[124:127]
	v_mfma_f32_16x16x32_bf16 v[120:123], v[154:157], v[184:187], v[120:123]
	v_mfma_f32_16x16x32_bf16 v[108:111], v[140:143], v[192:195], v[108:111]
	v_mfma_f32_16x16x32_bf16 v[104:107], v[154:157], v[192:195], v[104:107]
	v_mfma_f32_16x16x32_bf16 v[92:95], v[140:143], v[222:225], v[92:95]
	v_mfma_f32_16x16x32_bf16 v[88:91], v[154:157], v[222:225], v[88:91]
	v_mfma_f32_16x16x32_bf16 v[76:79], v[140:143], v[230:233], v[76:79]
	v_mfma_f32_16x16x32_bf16 v[72:75], v[154:157], v[230:233], v[72:75]
	v_mfma_f32_16x16x32_bf16 v[124:127], v[150:153], v[188:191], v[124:127]
	v_mfma_f32_16x16x32_bf16 v[120:123], v[164:167], v[188:191], v[120:123]
	v_mfma_f32_16x16x32_bf16 v[108:111], v[150:153], v[196:199], v[108:111]
	v_mfma_f32_16x16x32_bf16 v[104:107], v[164:167], v[196:199], v[104:107]
	v_mfma_f32_16x16x32_bf16 v[92:95], v[150:153], v[226:229], v[92:95]
	v_mfma_f32_16x16x32_bf16 v[88:91], v[164:167], v[226:229], v[88:91]
	v_mfma_f32_16x16x32_bf16 v[76:79], v[150:153], v[234:237], v[76:79]
	v_mfma_f32_16x16x32_bf16 v[72:75], v[164:167], v[234:237], v[72:75]
	v_mfma_f32_16x16x32_bf16 v[116:119], v[168:171], v[184:187], v[116:119]
	v_mfma_f32_16x16x32_bf16 v[112:115], v[176:179], v[184:187], v[112:115]
	v_mfma_f32_16x16x32_bf16 v[100:103], v[168:171], v[192:195], v[100:103]
	v_mfma_f32_16x16x32_bf16 v[96:99], v[176:179], v[192:195], v[96:99]
	v_mfma_f32_16x16x32_bf16 v[84:87], v[168:171], v[222:225], v[84:87]
	v_mfma_f32_16x16x32_bf16 v[80:83], v[176:179], v[222:225], v[80:83]
	v_mfma_f32_16x16x32_bf16 v[68:71], v[168:171], v[230:233], v[68:71]
	v_mfma_f32_16x16x32_bf16 v[64:67], v[176:179], v[230:233], v[64:67]
	v_mfma_f32_16x16x32_bf16 v[116:119], v[172:175], v[188:191], v[116:119]
	v_mfma_f32_16x16x32_bf16 v[112:115], v[180:183], v[188:191], v[112:115]
	v_mfma_f32_16x16x32_bf16 v[100:103], v[172:175], v[196:199], v[100:103]
	v_mfma_f32_16x16x32_bf16 v[96:99], v[180:183], v[196:199], v[96:99]
	v_mfma_f32_16x16x32_bf16 v[84:87], v[172:175], v[226:229], v[84:87]
	v_mfma_f32_16x16x32_bf16 v[80:83], v[180:183], v[226:229], v[80:83]
	v_mfma_f32_16x16x32_bf16 v[68:71], v[172:175], v[234:237], v[68:71]
	v_mfma_f32_16x16x32_bf16 v[64:67], v[180:183], v[234:237], v[64:67]
	s_barrier
	s_add_i32 s52, s88, s59
	s_mov_b32 m0, s52
	ds_read_b128 v[184:187], v149 offset:49152
	ds_read_b128 v[188:191], v149 offset:50176
	ds_read_b128 v[192:195], v149 offset:51200
	ds_read_b128 v[196:199], v149 offset:52224
	ds_read_b128 v[222:225], v149 offset:53248
	ds_read_b128 v[226:229], v149 offset:54272
	ds_read_b128 v[230:233], v149 offset:55296
	ds_read_b128 v[234:237], v149 offset:56320
	s_add_u32 s4, s4, 0x80
	s_addc_u32 s5, s5, 0
	global_load_lds_dwordx4 v130, s[4:5]
	s_add_i32 m0, s52, 0x2000
	s_add_i32 s52, s89, s59
	global_load_lds_dwordx4 v134, s[4:5]
	s_add_u32 s4, s4, 0x40000
	s_addc_u32 s5, s5, 0
	s_mov_b32 m0, s52
	s_nop 0
	global_load_lds_dwordx4 v130, s[4:5]
	s_add_i32 m0, s52, 0x2000
	s_nop 0
	global_load_lds_dwordx4 v134, s[4:5]
	s_mov_b32 m0, s84
	s_nop 0
	global_load_lds_dwordx4 v128, s[98:99]
	s_mov_b32 m0, s85
	s_nop 0
	global_load_lds_dwordx4 v132, s[98:99]
	s_waitcnt vmcnt(8)
	s_waitcnt lgkmcnt(0)
	s_barrier
	s_waitcnt lgkmcnt(0)
	v_mfma_f32_16x16x32_bf16 v[60:63], v[140:143], v[184:187], v[60:63]
	v_mfma_f32_16x16x32_bf16 v[56:59], v[154:157], v[184:187], v[56:59]
	v_mfma_f32_16x16x32_bf16 v[44:47], v[140:143], v[192:195], v[44:47]
	v_mfma_f32_16x16x32_bf16 v[40:43], v[154:157], v[192:195], v[40:43]
	v_mfma_f32_16x16x32_bf16 v[28:31], v[140:143], v[222:225], v[28:31]
	v_mfma_f32_16x16x32_bf16 v[24:27], v[154:157], v[222:225], v[24:27]
	v_mfma_f32_16x16x32_bf16 v[12:15], v[140:143], v[230:233], v[12:15]
	v_mfma_f32_16x16x32_bf16 v[8:11], v[154:157], v[230:233], v[8:11]
	v_mfma_f32_16x16x32_bf16 v[60:63], v[150:153], v[188:191], v[60:63]
	v_mfma_f32_16x16x32_bf16 v[56:59], v[164:167], v[188:191], v[56:59]
	v_mfma_f32_16x16x32_bf16 v[44:47], v[150:153], v[196:199], v[44:47]
	v_mfma_f32_16x16x32_bf16 v[40:43], v[164:167], v[196:199], v[40:43]
	v_mfma_f32_16x16x32_bf16 v[28:31], v[150:153], v[226:229], v[28:31]
	v_mfma_f32_16x16x32_bf16 v[24:27], v[164:167], v[226:229], v[24:27]
	v_mfma_f32_16x16x32_bf16 v[12:15], v[150:153], v[234:237], v[12:15]
	v_mfma_f32_16x16x32_bf16 v[8:11], v[164:167], v[234:237], v[8:11]
	v_mfma_f32_16x16x32_bf16 v[52:55], v[168:171], v[184:187], v[52:55]
	v_mfma_f32_16x16x32_bf16 v[48:51], v[176:179], v[184:187], v[48:51]
	v_mfma_f32_16x16x32_bf16 v[36:39], v[168:171], v[192:195], v[36:39]
	v_mfma_f32_16x16x32_bf16 v[32:35], v[176:179], v[192:195], v[32:35]
	v_mfma_f32_16x16x32_bf16 v[20:23], v[168:171], v[222:225], v[20:23]
	v_mfma_f32_16x16x32_bf16 v[16:19], v[176:179], v[222:225], v[16:19]
	v_mfma_f32_16x16x32_bf16 v[4:7], v[168:171], v[230:233], v[4:7]
	v_mfma_f32_16x16x32_bf16 v[0:3], v[176:179], v[230:233], v[0:3]
	v_mfma_f32_16x16x32_bf16 v[52:55], v[172:175], v[188:191], v[52:55]
	v_mfma_f32_16x16x32_bf16 v[48:51], v[180:183], v[188:191], v[48:51]
	v_mfma_f32_16x16x32_bf16 v[36:39], v[172:175], v[196:199], v[36:39]
	v_mfma_f32_16x16x32_bf16 v[32:35], v[180:183], v[196:199], v[32:35]
	v_mfma_f32_16x16x32_bf16 v[20:23], v[172:175], v[226:229], v[20:23]
	v_mfma_f32_16x16x32_bf16 v[16:19], v[180:183], v[226:229], v[16:19]
	v_mfma_f32_16x16x32_bf16 v[4:7], v[172:175], v[234:237], v[4:7]
	v_mfma_f32_16x16x32_bf16 v[0:3], v[180:183], v[234:237], v[0:3]
	s_barrier
	s_add_i32 s87, s87, 2
	s_add_u32 s82, s82, 0x100
	s_addc_u32 s83, s83, 0
	s_add_u32 s29, s29, 0x100
	s_addc_u32 s43, s43, 0
	s_cmp_gt_u32 s87, 13
	s_cbranch_scc0 .LBB0_86
	s_and_b64 vcc, exec, s[12:13]
	s_cbranch_vccz .LBB0_89
	s_barrier

; #define PG8_STAGE(bufoff, gbase, voff) do { _Pragma("unroll") for (int _i = 0; _i < 2; ++_i) \
;         __builtin_amdgcn_global_load_lds((const unsigned*)((const char*)(gbase) + (voff)[_i]), (PG8_LAS unsigned*)(lds + (bufoff) + ldsw + _i * 8192), 16, 0, 0); } while (0)
; #define PG8_LDA(dst, b, h) do { _Pragma("unroll") for (int m = 0; m < 4; ++m) _Pragma("unroll") for (int k = 0; k < 2; ++k) dst[m][k] = *(const PG8_LAS bf16x8*)(lds + PG8_SA(b, h) + aoff + m * 2048 + k * 1024); } while (0)
; #define PG8_LDB(dst, b, h) do { _Pragma("unroll") for (int n = 0; n < 2; ++n) _Pragma("unroll") for (int k = 0; k < 2; ++k) dst[n][k] = *(const PG8_LAS bf16x8*)(lds + PG8_SB(b, h) + boff + n * 2048 + k * 1024); } while (0)
; #define PG8_MMA(ai, bj, At, Bt) do { __builtin_amdgcn_s_setprio(1); _Pragma("unroll") for (int m = 0; m < 4; ++m) _Pragma("unroll") for (int n = 0; n < 2; ++n) _Pragma("unroll") for (int k = 0; k < 2; ++k) \
;         acc[ai][bj][m][n] = __builtin_amdgcn_mfma_f32_16x16x32_bf16(Bt[n][k], At[m][k], acc[ai][bj][m][n], 0, 0, 0); __builtin_amdgcn_s_setprio(0); } while (0)
; #define PG8_WAIT_V(n) asm volatile("s_waitcnt vmcnt(" #n ")" ::: "memory")
; #define PG8_WAIT_L(n) asm volatile("s_waitcnt lgkmcnt(" #n ")" ::: "memory")
; #define PG8_BAR __builtin_amdgcn_s_barrier()
; template <class Epi, class Sched, bool ALIGN_EPI = false, bool SP2 = false>
; __device__ __forceinline__ void gemm_phase(PG8_LAS unsigned char* lds, const Gemm g, const Sched& S, const Epi& E) {
;     ...
;             const char* a1 = cA + (size_t)(t + 1) * kstep;
;             const char* a2 = last ? nA : cA + (size_t)(t + 2) * kstep; const char* b2 = last ? nB : cB + (size_t)(t + 2) * kstep;
;             const char* a3 = a2 + kstep; const char* b3 = b2 + kstep;
;             if (last && has_next) S.a_ready(nxt);
;             if constexpr (SP2) {
;             PG8_LDB(B0, 0, 0); PG8_LDB(B1, 0, 1); PG8_SCHED; PG8_LDA(At, 0, 0); PG8_STAGE(PG8_SA(1, 1), a1 + hstep, voffA);
;             PG8_WAIT_V(8); PG8_WAIT_L(0); PG8_BAR; PG8_MMA(0, 0, At, B0); PG8_MMA(0, 1, At, B1); PG8_BAR; PG8_SCHED;
;             PG8_LDA(At, 0, 1); PG8_STAGE(PG8_SB(0, 0), b2, voffB); PG8_STAGE(PG8_SB(0, 1), b2 + hstep, voffB); PG8_STAGE(PG8_SA(0, 0), a2, voffA);
;             PG8_WAIT_V(8); PG8_WAIT_L(0); PG8_BAR; PG8_MMA(1, 0, At, B0); PG8_MMA(1, 1, At, B1); PG8_BAR; PG8_SCHED;
.LBB0_322:
	s_add_i32 s56, 0, 0x10000
	s_add_i32 vcc_lo, 0, 0x14000
	s_waitcnt lgkmcnt(0)
	ds_read_b128 v[154:157], v246
	ds_read_b128 v[164:167], v246 offset:1024
	ds_read_b128 v[168:171], v246 offset:2048
	ds_read_b128 v[172:175], v246 offset:3072
	ds_read_b128 v[176:179], v246 offset:16384
	ds_read_b128 v[180:183], v246 offset:17408
	ds_read_b128 v[184:187], v246 offset:18432
	ds_read_b128 v[188:191], v246 offset:19456
	s_add_i32 m0, s89, 0xc000
	ds_read_b128 v[192:195], v145
	ds_read_b128 v[196:199], v145 offset:1024
	ds_read_b128 v[222:225], v145 offset:2048
	ds_read_b128 v[226:229], v145 offset:3072
	ds_read_b128 v[230:233], v145 offset:4096
	ds_read_b128 v[234:237], v145 offset:5120
	ds_read_b128 v[238:241], v145 offset:6144
	ds_read_b128 v[242:245], v145 offset:7168
	global_load_lds_dwordx4 v150, s[14:15]
	s_add_i32 m0, s89, 0xe000
	s_nop 0
	global_load_lds_dwordx4 v152, s[14:15]
	s_add_u32 s4, s14, 0xfff80080
	s_addc_u32 s5, s15, -1
	s_cmp_eq_u32 s55, 28
	s_cselect_b32 s53, s1, s5
	s_cselect_b32 s52, s28, s4
	s_cselect_b32 s5, s29, s54
	s_cselect_b32 s4, s43, s45
	s_waitcnt vmcnt(8)
	s_waitcnt lgkmcnt(0)
	s_barrier
	s_waitcnt lgkmcnt(0)
	v_mfma_f32_16x16x32_bf16 v[124:127], v[154:157], v[192:195], v[124:127]
	v_mfma_f32_16x16x32_bf16 v[120:123], v[168:171], v[192:195], v[120:123]
	v_mfma_f32_16x16x32_bf16 v[116:119], v[154:157], v[222:225], v[116:119]
	v_mfma_f32_16x16x32_bf16 v[112:115], v[168:171], v[222:225], v[112:115]
	v_mfma_f32_16x16x32_bf16 v[108:111], v[154:157], v[230:233], v[108:111]
	v_mfma_f32_16x16x32_bf16 v[104:107], v[168:171], v[230:233], v[104:107]
	v_mfma_f32_16x16x32_bf16 v[100:103], v[154:157], v[238:241], v[100:103]
	v_mfma_f32_16x16x32_bf16 v[96:99], v[168:171], v[238:241], v[96:99]
	v_mfma_f32_16x16x32_bf16 v[124:127], v[164:167], v[196:199], v[124:127]
	v_mfma_f32_16x16x32_bf16 v[120:123], v[172:175], v[196:199], v[120:123]
	v_mfma_f32_16x16x32_bf16 v[116:119], v[164:167], v[226:229], v[116:119]
	v_mfma_f32_16x16x32_bf16 v[112:115], v[172:175], v[226:229], v[112:115]
	v_mfma_f32_16x16x32_bf16 v[108:111], v[164:167], v[234:237], v[108:111]
	v_mfma_f32_16x16x32_bf16 v[104:107], v[172:175], v[234:237], v[104:107]
	v_mfma_f32_16x16x32_bf16 v[100:103], v[164:167], v[242:245], v[100:103]
	v_mfma_f32_16x16x32_bf16 v[96:99], v[172:175], v[242:245], v[96:99]
	v_mfma_f32_16x16x32_bf16 v[92:95], v[176:179], v[192:195], v[92:95]
	v_mfma_f32_16x16x32_bf16 v[88:91], v[184:187], v[192:195], v[88:91]
	v_mfma_f32_16x16x32_bf16 v[84:87], v[176:179], v[222:225], v[84:87]
	v_mfma_f32_16x16x32_bf16 v[80:83], v[184:187], v[222:225], v[80:83]
	v_mfma_f32_16x16x32_bf16 v[76:79], v[176:179], v[230:233], v[76:79]
	v_mfma_f32_16x16x32_bf16 v[72:75], v[184:187], v[230:233], v[72:75]
	v_mfma_f32_16x16x32_bf16 v[68:71], v[176:179], v[238:241], v[68:71]
	v_mfma_f32_16x16x32_bf16 v[64:67], v[184:187], v[238:241], v[64:67]
	v_mfma_f32_16x16x32_bf16 v[92:95], v[180:183], v[196:199], v[92:95]
	v_mfma_f32_16x16x32_bf16 v[88:91], v[188:191], v[196:199], v[88:91]
	v_mfma_f32_16x16x32_bf16 v[84:87], v[180:183], v[226:229], v[84:87]
	v_mfma_f32_16x16x32_bf16 v[80:83], v[188:191], v[226:229], v[80:83]
	v_mfma_f32_16x16x32_bf16 v[76:79], v[180:183], v[234:237], v[76:79]
	v_mfma_f32_16x16x32_bf16 v[72:75], v[188:191], v[234:237], v[72:75]
	v_mfma_f32_16x16x32_bf16 v[68:71], v[180:183], v[242:245], v[68:71]
	v_mfma_f32_16x16x32_bf16 v[64:67], v[188:191], v[242:245], v[64:67]
	s_barrier
	s_add_i32 s56, s56, s63
	s_mov_b32 m0, s56
	ds_read_b128 v[192:195], v145 offset:16384
	ds_read_b128 v[196:199], v145 offset:17408
	ds_read_b128 v[222:225], v145 offset:18432
	ds_read_b128 v[226:229], v145 offset:19456
	ds_read_b128 v[230:233], v145 offset:20480
	ds_read_b128 v[234:237], v145 offset:21504
	ds_read_b128 v[238:241], v145 offset:22528
	ds_read_b128 v[242:245], v145 offset:23552
	global_load_lds_dwordx4 v130, s[4:5]
	s_add_i32 m0, s56, 0x2000
	s_add_u32 s56, s4, 0x80000
	s_addc_u32 s57, s5, 0
	s_add_i32 vcc_lo, vcc_lo, s63
	global_load_lds_dwordx4 v134, s[4:5]
	s_mov_b32 m0, vcc_lo
	s_nop 0
	global_load_lds_dwordx4 v130, s[56:57]
	s_add_i32 m0, vcc_lo, 0x2000
	s_nop 0
	global_load_lds_dwordx4 v134, s[56:57]
	s_mov_b32 m0, s89
	s_nop 0
	global_load_lds_dwordx4 v128, s[52:53]
	s_mov_b32 m0, s91
	s_nop 0
	global_load_lds_dwordx4 v132, s[52:53]
	s_add_u32 s98, s52, 0x80
	s_addc_u32 s99, s53, 0
	s_waitcnt vmcnt(8)
	s_waitcnt lgkmcnt(0)
	s_barrier
	s_waitcnt lgkmcnt(0)
	v_mfma_f32_16x16x32_bf16 v[60:63], v[154:157], v[192:195], v[60:63]
	v_mfma_f32_16x16x32_bf16 v[56:59], v[168:171], v[192:195], v[56:59]
	v_mfma_f32_16x16x32_bf16 v[52:55], v[154:157], v[222:225], v[52:55]
	v_mfma_f32_16x16x32_bf16 v[48:51], v[168:171], v[222:225], v[48:51]
	v_mfma_f32_16x16x32_bf16 v[44:47], v[154:157], v[230:233], v[44:47]
	v_mfma_f32_16x16x32_bf16 v[40:43], v[168:171], v[230:233], v[40:43]
	v_mfma_f32_16x16x32_bf16 v[36:39], v[154:157], v[238:241], v[36:39]
	v_mfma_f32_16x16x32_bf16 v[32:35], v[168:171], v[238:241], v[32:35]
	v_mfma_f32_16x16x32_bf16 v[60:63], v[164:167], v[196:199], v[60:63]
	v_mfma_f32_16x16x32_bf16 v[56:59], v[172:175], v[196:199], v[56:59]
	v_mfma_f32_16x16x32_bf16 v[52:55], v[164:167], v[226:229], v[52:55]
	v_mfma_f32_16x16x32_bf16 v[48:51], v[172:175], v[226:229], v[48:51]
	v_mfma_f32_16x16x32_bf16 v[44:47], v[164:167], v[234:237], v[44:47]
	v_mfma_f32_16x16x32_bf16 v[40:43], v[172:175], v[234:237], v[40:43]
	v_mfma_f32_16x16x32_bf16 v[36:39], v[164:167], v[242:245], v[36:39]
	v_mfma_f32_16x16x32_bf16 v[32:35], v[172:175], v[242:245], v[32:35]
	v_mfma_f32_16x16x32_bf16 v[28:31], v[176:179], v[192:195], v[28:31]
	v_mfma_f32_16x16x32_bf16 v[24:27], v[184:187], v[192:195], v[24:27]
	v_mfma_f32_16x16x32_bf16 v[20:23], v[176:179], v[222:225], v[20:23]
	v_mfma_f32_16x16x32_bf16 v[16:19], v[184:187], v[222:225], v[16:19]
	v_mfma_f32_16x16x32_bf16 v[12:15], v[176:179], v[230:233], v[12:15]
	v_mfma_f32_16x16x32_bf16 v[8:11], v[184:187], v[230:233], v[8:11]
	v_mfma_f32_16x16x32_bf16 v[4:7], v[176:179], v[238:241], v[4:7]
	v_mfma_f32_16x16x32_bf16 v[0:3], v[184:187], v[238:241], v[0:3]
	v_mfma_f32_16x16x32_bf16 v[28:31], v[180:183], v[196:199], v[28:31]
	v_mfma_f32_16x16x32_bf16 v[24:27], v[188:191], v[196:199], v[24:27]
	v_mfma_f32_16x16x32_bf16 v[20:23], v[180:183], v[226:229], v[20:23]
	v_mfma_f32_16x16x32_bf16 v[16:19], v[188:191], v[226:229], v[16:19]
	v_mfma_f32_16x16x32_bf16 v[12:15], v[180:183], v[234:237], v[12:15]
	v_mfma_f32_16x16x32_bf16 v[8:11], v[188:191], v[234:237], v[8:11]
	v_mfma_f32_16x16x32_bf16 v[4:7], v[180:183], v[242:245], v[4:7]
	v_mfma_f32_16x16x32_bf16 v[0:3], v[188:191], v[242:245], v[0:3]
	s_barrier
; #define PG8_STAGE(bufoff, gbase, voff) do { _Pragma("unroll") for (int _i = 0; _i < 2; ++_i) \
;         __builtin_amdgcn_global_load_lds((const unsigned*)((const char*)(gbase) + (voff)[_i]), (PG8_LAS unsigned*)(lds + (bufoff) + ldsw + _i * 8192), 16, 0, 0); } while (0)
; #define PG8_LDA(dst, b, h) do { _Pragma("unroll") for (int m = 0; m < 4; ++m) _Pragma("unroll") for (int k = 0; k < 2; ++k) dst[m][k] = *(const PG8_LAS bf16x8*)(lds + PG8_SA(b, h) + aoff + m * 2048 + k * 1024); } while (0)
; #define PG8_LDB(dst, b, h) do { _Pragma("unroll") for (int n = 0; n < 2; ++n) _Pragma("unroll") for (int k = 0; k < 2; ++k) dst[n][k] = *(const PG8_LAS bf16x8*)(lds + PG8_SB(b, h) + boff + n * 2048 + k * 1024); } while (0)
; #define PG8_MMA(ai, bj, At, Bt) do { __builtin_amdgcn_s_setprio(1); _Pragma("unroll") for (int m = 0; m < 4; ++m) _Pragma("unroll") for (int n = 0; n < 2; ++n) _Pragma("unroll") for (int k = 0; k < 2; ++k) \
;         acc[ai][bj][m][n] = __builtin_amdgcn_mfma_f32_16x16x32_bf16(Bt[n][k], At[m][k], acc[ai][bj][m][n], 0, 0, 0); __builtin_amdgcn_s_setprio(0); } while (0)
; #define PG8_WAIT_V(n) asm volatile("s_waitcnt vmcnt(" #n ")" ::: "memory")
; #define PG8_WAIT_L(n) asm volatile("s_waitcnt lgkmcnt(" #n ")" ::: "memory")
; #define PG8_BAR __builtin_amdgcn_s_barrier()
; #define PG8_SCHED __builtin_amdgcn_sched_barrier(0)
; template <class Epi, class Sched, bool ALIGN_EPI = false, bool SP2 = false>
; __device__ __forceinline__ void gemm_phase(PG8_LAS unsigned char* lds, const Gemm g, const Sched& S, const Epi& E) {
;     ...
;             PG8_LDB(B0, 1, 0); PG8_LDB(B1, 1, 1); PG8_SCHED; PG8_LDA(At, 1, 0); PG8_STAGE(PG8_SA(0, 1), a2 + hstep, voffA);
;             PG8_WAIT_V(8); PG8_WAIT_L(0); PG8_BAR; PG8_MMA(0, 0, At, B0); PG8_MMA(0, 1, At, B1); PG8_BAR; PG8_SCHED;
;             PG8_LDA(At, 1, 1); PG8_STAGE(PG8_SB(1, 0), b3, voffB); PG8_STAGE(PG8_SB(1, 1), b3 + hstep, voffB); PG8_STAGE(PG8_SA(1, 0), a3, voffA);
;             PG8_WAIT_V(8); PG8_WAIT_L(0); PG8_BAR; PG8_MMA(1, 0, At, B0); PG8_MMA(1, 1, At, B1); PG8_BAR; PG8_SCHED;
;     ...
;         if constexpr (ALIGN_EPI) { if (wr == 0) PG8_BAR; }
	s_add_i32 s56, 0, 0x18000
	s_add_i32 s57, 0, 0x1c000
	ds_read_b128 v[154:157], v246 offset:32768
	ds_read_b128 v[164:167], v246 offset:33792
	ds_read_b128 v[168:171], v246 offset:34816
	ds_read_b128 v[172:175], v246 offset:35840
	ds_read_b128 v[176:179], v246 offset:49152
	ds_read_b128 v[180:183], v246 offset:50176
	ds_read_b128 v[184:187], v246 offset:51200
	ds_read_b128 v[188:191], v246 offset:52224
	s_add_u32 s52, s52, 0x80000
	s_addc_u32 s53, s53, 0
	s_mov_b32 m0, s12
	ds_read_b128 v[192:195], v145 offset:32768
	ds_read_b128 v[196:199], v145 offset:33792
	ds_read_b128 v[222:225], v145 offset:34816
	ds_read_b128 v[226:229], v145 offset:35840
	ds_read_b128 v[230:233], v145 offset:36864
	ds_read_b128 v[234:237], v145 offset:37888
	ds_read_b128 v[238:241], v145 offset:38912
	ds_read_b128 v[242:245], v145 offset:39936
	global_load_lds_dwordx4 v128, s[52:53]
	s_mov_b32 m0, s13
	s_nop 0
	global_load_lds_dwordx4 v132, s[52:53]
	s_waitcnt vmcnt(8)
	s_waitcnt lgkmcnt(0)
	s_barrier
	s_waitcnt lgkmcnt(0)
	v_mfma_f32_16x16x32_bf16 v[124:127], v[154:157], v[192:195], v[124:127]
	v_mfma_f32_16x16x32_bf16 v[120:123], v[168:171], v[192:195], v[120:123]
	v_mfma_f32_16x16x32_bf16 v[116:119], v[154:157], v[222:225], v[116:119]
	v_mfma_f32_16x16x32_bf16 v[112:115], v[168:171], v[222:225], v[112:115]
	v_mfma_f32_16x16x32_bf16 v[108:111], v[154:157], v[230:233], v[108:111]
	v_mfma_f32_16x16x32_bf16 v[104:107], v[168:171], v[230:233], v[104:107]
	v_mfma_f32_16x16x32_bf16 v[100:103], v[154:157], v[238:241], v[100:103]
	v_mfma_f32_16x16x32_bf16 v[96:99], v[168:171], v[238:241], v[96:99]
	v_mfma_f32_16x16x32_bf16 v[124:127], v[164:167], v[196:199], v[124:127]
	v_mfma_f32_16x16x32_bf16 v[120:123], v[172:175], v[196:199], v[120:123]
	v_mfma_f32_16x16x32_bf16 v[116:119], v[164:167], v[226:229], v[116:119]
	v_mfma_f32_16x16x32_bf16 v[112:115], v[172:175], v[226:229], v[112:115]
	v_mfma_f32_16x16x32_bf16 v[108:111], v[164:167], v[234:237], v[108:111]
	v_mfma_f32_16x16x32_bf16 v[104:107], v[172:175], v[234:237], v[104:107]
	v_mfma_f32_16x16x32_bf16 v[100:103], v[164:167], v[242:245], v[100:103]
	v_mfma_f32_16x16x32_bf16 v[96:99], v[172:175], v[242:245], v[96:99]
	v_mfma_f32_16x16x32_bf16 v[92:95], v[176:179], v[192:195], v[92:95]
	v_mfma_f32_16x16x32_bf16 v[88:91], v[184:187], v[192:195], v[88:91]
	v_mfma_f32_16x16x32_bf16 v[84:87], v[176:179], v[222:225], v[84:87]
	v_mfma_f32_16x16x32_bf16 v[80:83], v[184:187], v[222:225], v[80:83]
	v_mfma_f32_16x16x32_bf16 v[76:79], v[176:179], v[230:233], v[76:79]
	v_mfma_f32_16x16x32_bf16 v[72:75], v[184:187], v[230:233], v[72:75]
	v_mfma_f32_16x16x32_bf16 v[68:71], v[176:179], v[238:241], v[68:71]
	v_mfma_f32_16x16x32_bf16 v[64:67], v[184:187], v[238:241], v[64:67]
	v_mfma_f32_16x16x32_bf16 v[92:95], v[180:183], v[196:199], v[92:95]
	v_mfma_f32_16x16x32_bf16 v[88:91], v[188:191], v[196:199], v[88:91]
	v_mfma_f32_16x16x32_bf16 v[84:87], v[180:183], v[226:229], v[84:87]
	v_mfma_f32_16x16x32_bf16 v[80:83], v[188:191], v[226:229], v[80:83]
	v_mfma_f32_16x16x32_bf16 v[76:79], v[180:183], v[234:237], v[76:79]
	v_mfma_f32_16x16x32_bf16 v[72:75], v[188:191], v[234:237], v[72:75]
	v_mfma_f32_16x16x32_bf16 v[68:71], v[180:183], v[242:245], v[68:71]
	v_mfma_f32_16x16x32_bf16 v[64:67], v[188:191], v[242:245], v[64:67]
	s_barrier
	s_add_i32 s52, s56, s63
	s_mov_b32 m0, s52
	ds_read_b128 v[192:195], v145 offset:49152
	ds_read_b128 v[196:199], v145 offset:50176
	ds_read_b128 v[222:225], v145 offset:51200
	ds_read_b128 v[226:229], v145 offset:52224
	ds_read_b128 v[230:233], v145 offset:53248
	ds_read_b128 v[234:237], v145 offset:54272
	ds_read_b128 v[238:241], v145 offset:55296
	ds_read_b128 v[242:245], v145 offset:56320
	s_add_u32 s4, s4, 0x80
	s_addc_u32 s5, s5, 0
	global_load_lds_dwordx4 v130, s[4:5]
	s_add_i32 m0, s52, 0x2000
	s_add_i32 s52, s57, s63
	global_load_lds_dwordx4 v134, s[4:5]
	s_add_u32 s4, s4, 0x80000
	s_addc_u32 s5, s5, 0
	s_mov_b32 m0, s52
	s_nop 0
	global_load_lds_dwordx4 v130, s[4:5]
	s_add_i32 m0, s52, 0x2000
	s_nop 0
	global_load_lds_dwordx4 v134, s[4:5]
	s_mov_b32 m0, s78
	s_nop 0
	global_load_lds_dwordx4 v128, s[98:99]
	s_mov_b32 m0, s79
	s_nop 0
	global_load_lds_dwordx4 v132, s[98:99]
	s_waitcnt vmcnt(8)
	s_waitcnt lgkmcnt(0)
	s_barrier
	s_waitcnt lgkmcnt(0)
	v_mfma_f32_16x16x32_bf16 v[60:63], v[154:157], v[192:195], v[60:63]
	v_mfma_f32_16x16x32_bf16 v[56:59], v[168:171], v[192:195], v[56:59]
	v_mfma_f32_16x16x32_bf16 v[52:55], v[154:157], v[222:225], v[52:55]
	v_mfma_f32_16x16x32_bf16 v[48:51], v[168:171], v[222:225], v[48:51]
	v_mfma_f32_16x16x32_bf16 v[44:47], v[154:157], v[230:233], v[44:47]
	v_mfma_f32_16x16x32_bf16 v[40:43], v[168:171], v[230:233], v[40:43]
	v_mfma_f32_16x16x32_bf16 v[36:39], v[154:157], v[238:241], v[36:39]
	v_mfma_f32_16x16x32_bf16 v[32:35], v[168:171], v[238:241], v[32:35]
	v_mfma_f32_16x16x32_bf16 v[60:63], v[164:167], v[196:199], v[60:63]
	v_mfma_f32_16x16x32_bf16 v[56:59], v[172:175], v[196:199], v[56:59]
	v_mfma_f32_16x16x32_bf16 v[52:55], v[164:167], v[226:229], v[52:55]
	v_mfma_f32_16x16x32_bf16 v[48:51], v[172:175], v[226:229], v[48:51]
	v_mfma_f32_16x16x32_bf16 v[44:47], v[164:167], v[234:237], v[44:47]
	v_mfma_f32_16x16x32_bf16 v[40:43], v[172:175], v[234:237], v[40:43]
	v_mfma_f32_16x16x32_bf16 v[36:39], v[164:167], v[242:245], v[36:39]
	v_mfma_f32_16x16x32_bf16 v[32:35], v[172:175], v[242:245], v[32:35]
	v_mfma_f32_16x16x32_bf16 v[28:31], v[176:179], v[192:195], v[28:31]
	v_mfma_f32_16x16x32_bf16 v[24:27], v[184:187], v[192:195], v[24:27]
	v_mfma_f32_16x16x32_bf16 v[20:23], v[176:179], v[222:225], v[20:23]
	v_mfma_f32_16x16x32_bf16 v[16:19], v[184:187], v[222:225], v[16:19]
	v_mfma_f32_16x16x32_bf16 v[12:15], v[176:179], v[230:233], v[12:15]
	v_mfma_f32_16x16x32_bf16 v[8:11], v[184:187], v[230:233], v[8:11]
	v_mfma_f32_16x16x32_bf16 v[4:7], v[176:179], v[238:241], v[4:7]
	v_mfma_f32_16x16x32_bf16 v[0:3], v[184:187], v[238:241], v[0:3]
	v_mfma_f32_16x16x32_bf16 v[28:31], v[180:183], v[196:199], v[28:31]
	v_mfma_f32_16x16x32_bf16 v[24:27], v[188:191], v[196:199], v[24:27]
	v_mfma_f32_16x16x32_bf16 v[20:23], v[180:183], v[226:229], v[20:23]
	v_mfma_f32_16x16x32_bf16 v[16:19], v[188:191], v[226:229], v[16:19]
	v_mfma_f32_16x16x32_bf16 v[12:15], v[180:183], v[234:237], v[12:15]
	v_mfma_f32_16x16x32_bf16 v[8:11], v[188:191], v[234:237], v[8:11]
	v_mfma_f32_16x16x32_bf16 v[4:7], v[180:183], v[242:245], v[4:7]
	v_mfma_f32_16x16x32_bf16 v[0:3], v[188:191], v[242:245], v[0:3]
	s_barrier
	s_add_i32 s55, s55, 2
	s_add_u32 s14, s14, 0x100
	s_addc_u32 s15, s15, 0
	s_add_u32 s45, s45, 0x100
	s_addc_u32 s54, s54, 0
	s_cmp_gt_u32 s55, 29
	s_cbranch_scc0 .LBB0_322
	s_and_b64 vcc, exec, s[82:83]
	s_cbranch_vccz .LBB0_325
	s_barrier

; #define PG8_STAGE(bufoff, gbase, voff) do { _Pragma("unroll") for (int _i = 0; _i < 2; ++_i) \
;         __builtin_amdgcn_global_load_lds((const unsigned*)((const char*)(gbase) + (voff)[_i]), (PG8_LAS unsigned*)(lds + (bufoff) + ldsw + _i * 8192), 16, 0, 0); } while (0)
; #define PG8_LDA(dst, b, h) do { _Pragma("unroll") for (int m = 0; m < 4; ++m) _Pragma("unroll") for (int k = 0; k < 2; ++k) dst[m][k] = *(const PG8_LAS bf16x8*)(lds + PG8_SA(b, h) + aoff + m * 2048 + k * 1024); } while (0)
; #define PG8_LDB(dst, b, h) do { _Pragma("unroll") for (int n = 0; n < 2; ++n) _Pragma("unroll") for (int k = 0; k < 2; ++k) dst[n][k] = *(const PG8_LAS bf16x8*)(lds + PG8_SB(b, h) + boff + n * 2048 + k * 1024); } while (0)
; #define PG8_MMA(ai, bj, At, Bt) do { __builtin_amdgcn_s_setprio(1); _Pragma("unroll") for (int m = 0; m < 4; ++m) _Pragma("unroll") for (int n = 0; n < 2; ++n) _Pragma("unroll") for (int k = 0; k < 2; ++k) \
;         acc[ai][bj][m][n] = __builtin_amdgcn_mfma_f32_16x16x32_bf16(Bt[n][k], At[m][k], acc[ai][bj][m][n], 0, 0, 0); __builtin_amdgcn_s_setprio(0); } while (0)
; #define PG8_WAIT_V(n) asm volatile("s_waitcnt vmcnt(" #n ")" ::: "memory")
; #define PG8_WAIT_L(n) asm volatile("s_waitcnt lgkmcnt(" #n ")" ::: "memory")
; #define PG8_BAR __builtin_amdgcn_s_barrier()
; template <class Epi, class Sched, bool ALIGN_EPI = false, bool SP2 = false>
; __device__ __forceinline__ void gemm_phase(PG8_LAS unsigned char* lds, const Gemm g, const Sched& S, const Epi& E) {
;     ...
;             const char* a1 = cA + (size_t)(t + 1) * kstep;
;             const char* a2 = last ? nA : cA + (size_t)(t + 2) * kstep; const char* b2 = last ? nB : cB + (size_t)(t + 2) * kstep;
;             const char* a3 = a2 + kstep; const char* b3 = b2 + kstep;
;             if (last && has_next) S.a_ready(nxt);
;             if constexpr (SP2) {
;             PG8_LDB(B0, 0, 0); PG8_LDB(B1, 0, 1); PG8_SCHED; PG8_LDA(At, 0, 0); PG8_STAGE(PG8_SA(1, 1), a1 + hstep, voffA);
;             PG8_WAIT_V(8); PG8_WAIT_L(0); PG8_BAR; PG8_MMA(0, 0, At, B0); PG8_MMA(0, 1, At, B1); PG8_BAR; PG8_SCHED;
;             PG8_LDA(At, 0, 1); PG8_STAGE(PG8_SB(0, 0), b2, voffB); PG8_STAGE(PG8_SB(0, 1), b2 + hstep, voffB); PG8_STAGE(PG8_SA(0, 0), a2, voffA);
;             PG8_WAIT_V(8); PG8_WAIT_L(0); PG8_BAR; PG8_MMA(1, 0, At, B0); PG8_MMA(1, 1, At, B1); PG8_BAR; PG8_SCHED;
.LBB0_849:
	s_add_i32 s76, 0, 0x10000
	s_add_i32 s78, 0, 0x14000
	ds_read_b128 v[144:147], v200
	ds_read_b128 v[148:151], v200 offset:1024
	ds_read_b128 v[152:155], v200 offset:2048
	ds_read_b128 v[156:159], v200 offset:3072
	ds_read_b128 v[164:167], v200 offset:16384
	ds_read_b128 v[168:171], v200 offset:17408
	ds_read_b128 v[172:175], v200 offset:18432
	ds_read_b128 v[176:179], v200 offset:19456
	s_add_i32 m0, s51, 0xc000
	ds_read_b128 v[180:183], v143
	ds_read_b128 v[184:187], v143 offset:1024
	ds_read_b128 v[188:191], v143 offset:2048
	ds_read_b128 v[192:195], v143 offset:3072
	ds_read_b128 v[196:199], v143 offset:4096
	ds_read_b128 v[222:225], v143 offset:5120
	ds_read_b128 v[226:229], v143 offset:6144
	ds_read_b128 v[230:233], v143 offset:7168
	global_load_lds_dwordx4 v134, s[70:71]
	s_add_i32 m0, s51, 0xe000
	s_nop 0
	global_load_lds_dwordx4 v136, s[70:71]
	s_add_u32 s4, s70, 0xfff80080
	s_addc_u32 s5, s71, -1
	s_cmp_eq_u32 s75, 28
	s_cselect_b32 s53, s11, s5
	s_cselect_b32 s52, s63, s4
	s_cselect_b32 s5, s13, s74
	s_cselect_b32 s4, s72, s73
	s_waitcnt vmcnt(8)
	s_waitcnt lgkmcnt(0)
	s_barrier
	s_waitcnt lgkmcnt(0)
	v_mfma_f32_16x16x32_bf16 v[124:127], v[144:147], v[180:183], v[124:127]
	v_mfma_f32_16x16x32_bf16 v[116:119], v[152:155], v[180:183], v[116:119]
	v_mfma_f32_16x16x32_bf16 v[108:111], v[144:147], v[188:191], v[108:111]
	v_mfma_f32_16x16x32_bf16 v[100:103], v[152:155], v[188:191], v[100:103]
	v_mfma_f32_16x16x32_bf16 v[92:95], v[144:147], v[196:199], v[92:95]
	v_mfma_f32_16x16x32_bf16 v[84:87], v[152:155], v[196:199], v[84:87]
	v_mfma_f32_16x16x32_bf16 v[76:79], v[144:147], v[226:229], v[76:79]
	v_mfma_f32_16x16x32_bf16 v[68:71], v[152:155], v[226:229], v[68:71]
	v_mfma_f32_16x16x32_bf16 v[124:127], v[148:151], v[184:187], v[124:127]
	v_mfma_f32_16x16x32_bf16 v[116:119], v[156:159], v[184:187], v[116:119]
	v_mfma_f32_16x16x32_bf16 v[108:111], v[148:151], v[192:195], v[108:111]
	v_mfma_f32_16x16x32_bf16 v[100:103], v[156:159], v[192:195], v[100:103]
	v_mfma_f32_16x16x32_bf16 v[92:95], v[148:151], v[222:225], v[92:95]
	v_mfma_f32_16x16x32_bf16 v[84:87], v[156:159], v[222:225], v[84:87]
	v_mfma_f32_16x16x32_bf16 v[76:79], v[148:151], v[230:233], v[76:79]
	v_mfma_f32_16x16x32_bf16 v[68:71], v[156:159], v[230:233], v[68:71]
	v_mfma_f32_16x16x32_bf16 v[120:123], v[164:167], v[180:183], v[120:123]
	v_mfma_f32_16x16x32_bf16 v[112:115], v[172:175], v[180:183], v[112:115]
	v_mfma_f32_16x16x32_bf16 v[104:107], v[164:167], v[188:191], v[104:107]
	v_mfma_f32_16x16x32_bf16 v[96:99], v[172:175], v[188:191], v[96:99]
	v_mfma_f32_16x16x32_bf16 v[88:91], v[164:167], v[196:199], v[88:91]
	v_mfma_f32_16x16x32_bf16 v[80:83], v[172:175], v[196:199], v[80:83]
	v_mfma_f32_16x16x32_bf16 v[72:75], v[164:167], v[226:229], v[72:75]
	v_mfma_f32_16x16x32_bf16 v[64:67], v[172:175], v[226:229], v[64:67]
	v_mfma_f32_16x16x32_bf16 v[120:123], v[168:171], v[184:187], v[120:123]
	v_mfma_f32_16x16x32_bf16 v[112:115], v[176:179], v[184:187], v[112:115]
	v_mfma_f32_16x16x32_bf16 v[104:107], v[168:171], v[192:195], v[104:107]
	v_mfma_f32_16x16x32_bf16 v[96:99], v[176:179], v[192:195], v[96:99]
	v_mfma_f32_16x16x32_bf16 v[88:91], v[168:171], v[222:225], v[88:91]
	v_mfma_f32_16x16x32_bf16 v[80:83], v[176:179], v[222:225], v[80:83]
	v_mfma_f32_16x16x32_bf16 v[72:75], v[168:171], v[230:233], v[72:75]
	v_mfma_f32_16x16x32_bf16 v[64:67], v[176:179], v[230:233], v[64:67]
	s_barrier
	s_add_i32 s76, s76, s24
	s_mov_b32 m0, s76
	ds_read_b128 v[180:183], v143 offset:16384
	ds_read_b128 v[184:187], v143 offset:17408
	ds_read_b128 v[188:191], v143 offset:18432
	ds_read_b128 v[192:195], v143 offset:19456
	ds_read_b128 v[196:199], v143 offset:20480
	ds_read_b128 v[222:225], v143 offset:21504
	ds_read_b128 v[226:229], v143 offset:22528
	ds_read_b128 v[230:233], v143 offset:23552
	global_load_lds_dwordx4 v160, s[4:5]
	s_add_i32 m0, s76, 0x2000
	s_add_u32 s76, s4, 0x80000
	s_addc_u32 s77, s5, 0
	s_add_i32 s78, s78, s24
	global_load_lds_dwordx4 v128, s[4:5]
	s_mov_b32 m0, s78
	s_nop 0
	global_load_lds_dwordx4 v160, s[76:77]
	s_add_i32 m0, s78, 0x2000
	s_nop 0
	global_load_lds_dwordx4 v128, s[76:77]
	s_mov_b32 m0, s51
	s_nop 0
	global_load_lds_dwordx4 v132, s[52:53]
	s_mov_b32 m0, s55
	s_nop 0
	global_load_lds_dwordx4 v130, s[52:53]
	s_add_u32 s98, s52, 0x80
	s_addc_u32 s99, s53, 0
	s_waitcnt vmcnt(8)
	s_waitcnt lgkmcnt(0)
	s_barrier
	s_waitcnt lgkmcnt(0)
	v_mfma_f32_16x16x32_bf16 v[60:63], v[144:147], v[180:183], v[60:63]
	v_mfma_f32_16x16x32_bf16 v[52:55], v[152:155], v[180:183], v[52:55]
	v_mfma_f32_16x16x32_bf16 v[44:47], v[144:147], v[188:191], v[44:47]
	v_mfma_f32_16x16x32_bf16 v[36:39], v[152:155], v[188:191], v[36:39]
	v_mfma_f32_16x16x32_bf16 v[28:31], v[144:147], v[196:199], v[28:31]
	v_mfma_f32_16x16x32_bf16 v[20:23], v[152:155], v[196:199], v[20:23]
	v_mfma_f32_16x16x32_bf16 v[12:15], v[144:147], v[226:229], v[12:15]
	v_mfma_f32_16x16x32_bf16 v[4:7], v[152:155], v[226:229], v[4:7]
	v_mfma_f32_16x16x32_bf16 v[60:63], v[148:151], v[184:187], v[60:63]
	v_mfma_f32_16x16x32_bf16 v[52:55], v[156:159], v[184:187], v[52:55]
	v_mfma_f32_16x16x32_bf16 v[44:47], v[148:151], v[192:195], v[44:47]
	v_mfma_f32_16x16x32_bf16 v[36:39], v[156:159], v[192:195], v[36:39]
	v_mfma_f32_16x16x32_bf16 v[28:31], v[148:151], v[222:225], v[28:31]
	v_mfma_f32_16x16x32_bf16 v[20:23], v[156:159], v[222:225], v[20:23]
	v_mfma_f32_16x16x32_bf16 v[12:15], v[148:151], v[230:233], v[12:15]
	v_mfma_f32_16x16x32_bf16 v[4:7], v[156:159], v[230:233], v[4:7]
	v_mfma_f32_16x16x32_bf16 v[56:59], v[164:167], v[180:183], v[56:59]
	v_mfma_f32_16x16x32_bf16 v[48:51], v[172:175], v[180:183], v[48:51]
	v_mfma_f32_16x16x32_bf16 v[40:43], v[164:167], v[188:191], v[40:43]
	v_mfma_f32_16x16x32_bf16 v[32:35], v[172:175], v[188:191], v[32:35]
	v_mfma_f32_16x16x32_bf16 v[24:27], v[164:167], v[196:199], v[24:27]
	v_mfma_f32_16x16x32_bf16 v[16:19], v[172:175], v[196:199], v[16:19]
	v_mfma_f32_16x16x32_bf16 v[8:11], v[164:167], v[226:229], v[8:11]
	v_mfma_f32_16x16x32_bf16 v[0:3], v[172:175], v[226:229], v[0:3]
	v_mfma_f32_16x16x32_bf16 v[56:59], v[168:171], v[184:187], v[56:59]
	v_mfma_f32_16x16x32_bf16 v[48:51], v[176:179], v[184:187], v[48:51]
	v_mfma_f32_16x16x32_bf16 v[40:43], v[168:171], v[192:195], v[40:43]
	v_mfma_f32_16x16x32_bf16 v[32:35], v[176:179], v[192:195], v[32:35]
	v_mfma_f32_16x16x32_bf16 v[24:27], v[168:171], v[222:225], v[24:27]
	v_mfma_f32_16x16x32_bf16 v[16:19], v[176:179], v[222:225], v[16:19]
	v_mfma_f32_16x16x32_bf16 v[8:11], v[168:171], v[230:233], v[8:11]
	v_mfma_f32_16x16x32_bf16 v[0:3], v[176:179], v[230:233], v[0:3]
	s_barrier
; #define PG8_STAGE(bufoff, gbase, voff) do { _Pragma("unroll") for (int _i = 0; _i < 2; ++_i) \
;         __builtin_amdgcn_global_load_lds((const unsigned*)((const char*)(gbase) + (voff)[_i]), (PG8_LAS unsigned*)(lds + (bufoff) + ldsw + _i * 8192), 16, 0, 0); } while (0)
; #define PG8_LDA(dst, b, h) do { _Pragma("unroll") for (int m = 0; m < 4; ++m) _Pragma("unroll") for (int k = 0; k < 2; ++k) dst[m][k] = *(const PG8_LAS bf16x8*)(lds + PG8_SA(b, h) + aoff + m * 2048 + k * 1024); } while (0)
; #define PG8_LDB(dst, b, h) do { _Pragma("unroll") for (int n = 0; n < 2; ++n) _Pragma("unroll") for (int k = 0; k < 2; ++k) dst[n][k] = *(const PG8_LAS bf16x8*)(lds + PG8_SB(b, h) + boff + n * 2048 + k * 1024); } while (0)
; #define PG8_MMA(ai, bj, At, Bt) do { __builtin_amdgcn_s_setprio(1); _Pragma("unroll") for (int m = 0; m < 4; ++m) _Pragma("unroll") for (int n = 0; n < 2; ++n) _Pragma("unroll") for (int k = 0; k < 2; ++k) \
;         acc[ai][bj][m][n] = __builtin_amdgcn_mfma_f32_16x16x32_bf16(Bt[n][k], At[m][k], acc[ai][bj][m][n], 0, 0, 0); __builtin_amdgcn_s_setprio(0); } while (0)
; #define PG8_WAIT_V(n) asm volatile("s_waitcnt vmcnt(" #n ")" ::: "memory")
; #define PG8_WAIT_L(n) asm volatile("s_waitcnt lgkmcnt(" #n ")" ::: "memory")
; #define PG8_BAR __builtin_amdgcn_s_barrier()
; #define PG8_SCHED __builtin_amdgcn_sched_barrier(0)
; template <class Epi, class Sched, bool ALIGN_EPI = false, bool SP2 = false>
; __device__ __forceinline__ void gemm_phase(PG8_LAS unsigned char* lds, const Gemm g, const Sched& S, const Epi& E) {
;     ...
;             PG8_LDB(B0, 1, 0); PG8_LDB(B1, 1, 1); PG8_SCHED; PG8_LDA(At, 1, 0); PG8_STAGE(PG8_SA(0, 1), a2 + hstep, voffA);
;             PG8_WAIT_V(8); PG8_WAIT_L(0); PG8_BAR; PG8_MMA(0, 0, At, B0); PG8_MMA(0, 1, At, B1); PG8_BAR; PG8_SCHED;
;             PG8_LDA(At, 1, 1); PG8_STAGE(PG8_SB(1, 0), b3, voffB); PG8_STAGE(PG8_SB(1, 1), b3 + hstep, voffB); PG8_STAGE(PG8_SA(1, 0), a3, voffA);
;             PG8_WAIT_V(8); PG8_WAIT_L(0); PG8_BAR; PG8_MMA(1, 0, At, B0); PG8_MMA(1, 1, At, B1); PG8_BAR; PG8_SCHED;
;     ...
;         if constexpr (ALIGN_EPI) { if (wr == 0) PG8_BAR; }
	s_add_i32 s76, 0, 0x18000
	s_add_i32 s77, 0, 0x1c000
	ds_read_b128 v[144:147], v200 offset:32768
	ds_read_b128 v[148:151], v200 offset:33792
	ds_read_b128 v[152:155], v200 offset:34816
	ds_read_b128 v[156:159], v200 offset:35840
	ds_read_b128 v[164:167], v200 offset:49152
	ds_read_b128 v[168:171], v200 offset:50176
	ds_read_b128 v[172:175], v200 offset:51200
	ds_read_b128 v[176:179], v200 offset:52224
	s_add_u32 s52, s52, 0x80000
	s_addc_u32 s53, s53, 0
	s_mov_b32 m0, s56
	ds_read_b128 v[180:183], v143 offset:32768
	ds_read_b128 v[184:187], v143 offset:33792
	ds_read_b128 v[188:191], v143 offset:34816
	ds_read_b128 v[192:195], v143 offset:35840
	ds_read_b128 v[196:199], v143 offset:36864
	ds_read_b128 v[222:225], v143 offset:37888
	ds_read_b128 v[226:229], v143 offset:38912
	ds_read_b128 v[230:233], v143 offset:39936
	global_load_lds_dwordx4 v132, s[52:53]
	s_mov_b32 m0, s57
	s_nop 0
	global_load_lds_dwordx4 v130, s[52:53]
	s_waitcnt vmcnt(8)
	s_waitcnt lgkmcnt(0)
	s_barrier
	s_waitcnt lgkmcnt(0)
	v_mfma_f32_16x16x32_bf16 v[124:127], v[144:147], v[180:183], v[124:127]
	v_mfma_f32_16x16x32_bf16 v[116:119], v[152:155], v[180:183], v[116:119]
	v_mfma_f32_16x16x32_bf16 v[108:111], v[144:147], v[188:191], v[108:111]
	v_mfma_f32_16x16x32_bf16 v[100:103], v[152:155], v[188:191], v[100:103]
	v_mfma_f32_16x16x32_bf16 v[92:95], v[144:147], v[196:199], v[92:95]
	v_mfma_f32_16x16x32_bf16 v[84:87], v[152:155], v[196:199], v[84:87]
	v_mfma_f32_16x16x32_bf16 v[76:79], v[144:147], v[226:229], v[76:79]
	v_mfma_f32_16x16x32_bf16 v[68:71], v[152:155], v[226:229], v[68:71]
	v_mfma_f32_16x16x32_bf16 v[124:127], v[148:151], v[184:187], v[124:127]
	v_mfma_f32_16x16x32_bf16 v[116:119], v[156:159], v[184:187], v[116:119]
	v_mfma_f32_16x16x32_bf16 v[108:111], v[148:151], v[192:195], v[108:111]
	v_mfma_f32_16x16x32_bf16 v[100:103], v[156:159], v[192:195], v[100:103]
	v_mfma_f32_16x16x32_bf16 v[92:95], v[148:151], v[222:225], v[92:95]
	v_mfma_f32_16x16x32_bf16 v[84:87], v[156:159], v[222:225], v[84:87]
	v_mfma_f32_16x16x32_bf16 v[76:79], v[148:151], v[230:233], v[76:79]
	v_mfma_f32_16x16x32_bf16 v[68:71], v[156:159], v[230:233], v[68:71]
	v_mfma_f32_16x16x32_bf16 v[120:123], v[164:167], v[180:183], v[120:123]
	v_mfma_f32_16x16x32_bf16 v[112:115], v[172:175], v[180:183], v[112:115]
	v_mfma_f32_16x16x32_bf16 v[104:107], v[164:167], v[188:191], v[104:107]
	v_mfma_f32_16x16x32_bf16 v[96:99], v[172:175], v[188:191], v[96:99]
	v_mfma_f32_16x16x32_bf16 v[88:91], v[164:167], v[196:199], v[88:91]
	v_mfma_f32_16x16x32_bf16 v[80:83], v[172:175], v[196:199], v[80:83]
	v_mfma_f32_16x16x32_bf16 v[72:75], v[164:167], v[226:229], v[72:75]
	v_mfma_f32_16x16x32_bf16 v[64:67], v[172:175], v[226:229], v[64:67]
	v_mfma_f32_16x16x32_bf16 v[120:123], v[168:171], v[184:187], v[120:123]
	v_mfma_f32_16x16x32_bf16 v[112:115], v[176:179], v[184:187], v[112:115]
	v_mfma_f32_16x16x32_bf16 v[104:107], v[168:171], v[192:195], v[104:107]
	v_mfma_f32_16x16x32_bf16 v[96:99], v[176:179], v[192:195], v[96:99]
	v_mfma_f32_16x16x32_bf16 v[88:91], v[168:171], v[222:225], v[88:91]
	v_mfma_f32_16x16x32_bf16 v[80:83], v[176:179], v[222:225], v[80:83]
	v_mfma_f32_16x16x32_bf16 v[72:75], v[168:171], v[230:233], v[72:75]
	v_mfma_f32_16x16x32_bf16 v[64:67], v[176:179], v[230:233], v[64:67]
	s_barrier
	s_add_i32 s52, s76, s24
	s_mov_b32 m0, s52
	ds_read_b128 v[180:183], v143 offset:49152
	ds_read_b128 v[184:187], v143 offset:50176
	ds_read_b128 v[188:191], v143 offset:51200
	ds_read_b128 v[192:195], v143 offset:52224
	ds_read_b128 v[196:199], v143 offset:53248
	ds_read_b128 v[222:225], v143 offset:54272
	ds_read_b128 v[226:229], v143 offset:55296
	ds_read_b128 v[230:233], v143 offset:56320
	s_add_u32 s4, s4, 0x80
	s_addc_u32 s5, s5, 0
	global_load_lds_dwordx4 v160, s[4:5]
	s_add_i32 m0, s52, 0x2000
	s_add_i32 s52, s77, s24
	global_load_lds_dwordx4 v128, s[4:5]
	s_add_u32 s4, s4, 0x80000
	s_addc_u32 s5, s5, 0
	s_mov_b32 m0, s52
	s_nop 0
	global_load_lds_dwordx4 v160, s[4:5]
	s_add_i32 m0, s52, 0x2000
	s_nop 0
	global_load_lds_dwordx4 v128, s[4:5]
	s_mov_b32 m0, s58
	s_nop 0
	global_load_lds_dwordx4 v132, s[98:99]
	s_mov_b32 m0, s59
	s_nop 0
	global_load_lds_dwordx4 v130, s[98:99]
	s_waitcnt vmcnt(8)
	s_waitcnt lgkmcnt(0)
	s_barrier
	s_waitcnt lgkmcnt(0)
	v_mfma_f32_16x16x32_bf16 v[60:63], v[144:147], v[180:183], v[60:63]
	v_mfma_f32_16x16x32_bf16 v[52:55], v[152:155], v[180:183], v[52:55]
	v_mfma_f32_16x16x32_bf16 v[44:47], v[144:147], v[188:191], v[44:47]
	v_mfma_f32_16x16x32_bf16 v[36:39], v[152:155], v[188:191], v[36:39]
	v_mfma_f32_16x16x32_bf16 v[28:31], v[144:147], v[196:199], v[28:31]
	v_mfma_f32_16x16x32_bf16 v[20:23], v[152:155], v[196:199], v[20:23]
	v_mfma_f32_16x16x32_bf16 v[12:15], v[144:147], v[226:229], v[12:15]
	v_mfma_f32_16x16x32_bf16 v[4:7], v[152:155], v[226:229], v[4:7]
	v_mfma_f32_16x16x32_bf16 v[60:63], v[148:151], v[184:187], v[60:63]
	v_mfma_f32_16x16x32_bf16 v[52:55], v[156:159], v[184:187], v[52:55]
	v_mfma_f32_16x16x32_bf16 v[44:47], v[148:151], v[192:195], v[44:47]
	v_mfma_f32_16x16x32_bf16 v[36:39], v[156:159], v[192:195], v[36:39]
	v_mfma_f32_16x16x32_bf16 v[28:31], v[148:151], v[222:225], v[28:31]
	v_mfma_f32_16x16x32_bf16 v[20:23], v[156:159], v[222:225], v[20:23]
	v_mfma_f32_16x16x32_bf16 v[12:15], v[148:151], v[230:233], v[12:15]
	v_mfma_f32_16x16x32_bf16 v[4:7], v[156:159], v[230:233], v[4:7]
	v_mfma_f32_16x16x32_bf16 v[56:59], v[164:167], v[180:183], v[56:59]
	v_mfma_f32_16x16x32_bf16 v[48:51], v[172:175], v[180:183], v[48:51]
	v_mfma_f32_16x16x32_bf16 v[40:43], v[164:167], v[188:191], v[40:43]
	v_mfma_f32_16x16x32_bf16 v[32:35], v[172:175], v[188:191], v[32:35]
	v_mfma_f32_16x16x32_bf16 v[24:27], v[164:167], v[196:199], v[24:27]
	v_mfma_f32_16x16x32_bf16 v[16:19], v[172:175], v[196:199], v[16:19]
	v_mfma_f32_16x16x32_bf16 v[8:11], v[164:167], v[226:229], v[8:11]
	v_mfma_f32_16x16x32_bf16 v[0:3], v[172:175], v[226:229], v[0:3]
	v_mfma_f32_16x16x32_bf16 v[56:59], v[168:171], v[184:187], v[56:59]
	v_mfma_f32_16x16x32_bf16 v[48:51], v[176:179], v[184:187], v[48:51]
	v_mfma_f32_16x16x32_bf16 v[40:43], v[168:171], v[192:195], v[40:43]
	v_mfma_f32_16x16x32_bf16 v[32:35], v[176:179], v[192:195], v[32:35]
	v_mfma_f32_16x16x32_bf16 v[24:27], v[168:171], v[222:225], v[24:27]
	v_mfma_f32_16x16x32_bf16 v[16:19], v[176:179], v[222:225], v[16:19]
	v_mfma_f32_16x16x32_bf16 v[8:11], v[168:171], v[230:233], v[8:11]
	v_mfma_f32_16x16x32_bf16 v[0:3], v[176:179], v[230:233], v[0:3]
	s_barrier
	s_add_i32 s75, s75, 2
	s_add_u32 s70, s70, 0x100
	s_addc_u32 s71, s71, 0
	s_add_u32 s73, s73, 0x100
	s_addc_u32 s74, s74, 0
	s_cmp_gt_u32 s75, 29
	s_cbranch_scc0 .LBB0_849
	s_and_b64 vcc, exec, s[8:9]
	s_cbranch_vccz .LBB0_852
	s_barrier
